# non-temporal (nt, L1-bypass) loads for the cold input/weight streams of the prologue phase P0 (transposes + adaLN GEMV): lifts the 32KB-in-flight-per-CU cap; on top of conv/GLU overlap, scan register
# speedup vs baseline: 1.0177x; 1.0177x over previous
.LBB0_26:
	s_lshl_b32 s52, s12, 1
	s_lshl_b32 s53, s13, 1
	v_or_b32_e32 v6, s53, v16
	s_add_i32 s60, s52, 4
	s_add_i32 s61, s53, 4
	v_mov_b32_e32 v29, v7
	s_add_i32 s63, s53, 8
	v_lshlrev_b64 v[42:43], 12, v[6:7]
	v_or_b32_e32 v28, s60, v3
	v_or_b32_e32 v6, s61, v16
	v_mov_b32_e32 v25, v7
	v_or_b32_e32 v24, s52, v3
	s_add_i32 s65, s53, 12
	v_lshlrev_b64 v[28:29], 12, v[28:29]
	v_lshlrev_b64 v[44:45], 12, v[6:7]
	v_or_b32_e32 v6, s63, v16
	s_add_i32 s62, s52, 8
	s_add_i32 s64, s52, 12
	s_add_i32 s67, s53, 16
	v_lshlrev_b64 v[24:25], 12, v[24:25]
	v_lshl_add_u64 v[42:43], v[14:15], 0, v[42:43]
	v_lshl_add_u64 v[28:29], v[14:15], 0, v[28:29]
	v_lshlrev_b64 v[46:47], 12, v[6:7]
	v_or_b32_e32 v6, s65, v16
	v_mov_b32_e32 v31, v7
	v_mov_b32_e32 v33, v7
	s_add_i32 s69, s53, 20
	v_or_b32_e32 v30, s62, v3
	v_or_b32_e32 v32, s64, v3
	v_lshl_add_u64 v[24:25], v[14:15], 0, v[24:25]
	v_lshl_add_u64 v[44:45], v[14:15], 0, v[44:45]
	global_load_dword v11, v[42:43], off nt
	global_load_dword v13, v[24:25], off nt
	global_load_dword v58, v[44:45], off nt
	global_load_dword v59, v[28:29], off nt
	v_lshlrev_b64 v[28:29], 12, v[6:7]
	v_or_b32_e32 v6, s67, v16
	s_add_i32 s66, s52, 16
	s_add_i32 s68, s52, 20
	s_add_i32 s71, s53, 24
	v_lshlrev_b64 v[30:31], 12, v[30:31]
	v_lshlrev_b64 v[32:33], 12, v[32:33]
	v_lshl_add_u64 v[24:25], v[14:15], 0, v[46:47]
	v_lshl_add_u64 v[28:29], v[14:15], 0, v[28:29]
	v_lshlrev_b64 v[42:43], 12, v[6:7]
	v_or_b32_e32 v6, s69, v16
	v_mov_b32_e32 v35, v7
	v_mov_b32_e32 v37, v7
	s_add_i32 s70, s52, 24
	s_add_i32 s72, s52, 28
	s_add_i32 s73, s53, 28
	v_or_b32_e32 v34, s66, v3
	v_or_b32_e32 v36, s68, v3
	v_lshl_add_u64 v[30:31], v[14:15], 0, v[30:31]
	v_lshl_add_u64 v[32:33], v[14:15], 0, v[32:33]
	global_load_dword v60, v[24:25], off nt
	global_load_dword v61, v[30:31], off nt
	global_load_dword v62, v[28:29], off nt
	global_load_dword v63, v[32:33], off nt
	v_lshlrev_b64 v[28:29], 12, v[6:7]
	v_or_b32_e32 v6, s71, v16
	v_mov_b32_e32 v39, v7
	v_mov_b32_e32 v41, v7
	v_or_b32_e32 v38, s70, v3
	v_or_b32_e32 v40, s72, v3
	v_lshlrev_b64 v[34:35], 12, v[34:35]
	v_lshlrev_b64 v[36:37], 12, v[36:37]
	v_lshl_add_u64 v[24:25], v[14:15], 0, v[42:43]
	v_lshl_add_u64 v[28:29], v[14:15], 0, v[28:29]
	v_lshlrev_b64 v[30:31], 12, v[6:7]
	v_or_b32_e32 v6, s73, v16
	v_lshlrev_b64 v[38:39], 12, v[38:39]
	v_lshlrev_b64 v[40:41], 12, v[40:41]
	v_lshl_add_u64 v[34:35], v[14:15], 0, v[34:35]
	v_lshl_add_u64 v[36:37], v[14:15], 0, v[36:37]
	global_load_dword v64, v[24:25], off nt
	global_load_dword v65, v[34:35], off nt
	global_load_dword v66, v[28:29], off nt
	global_load_dword v67, v[36:37], off nt
	v_lshl_add_u64 v[24:25], v[14:15], 0, v[30:31]
	v_lshlrev_b64 v[28:29], 12, v[6:7]
	v_lshl_add_u64 v[38:39], v[14:15], 0, v[38:39]
	v_lshl_add_u64 v[40:41], v[14:15], 0, v[40:41]
	v_lshl_add_u64 v[28:29], v[14:15], 0, v[28:29]
	global_load_dword v6, v[24:25], off nt
	global_load_dword v68, v[38:39], off nt
	global_load_dword v69, v[28:29], off nt
	global_load_dword v70, v[40:41], off nt
	v_or_b32_e32 v28, s52, v1
	v_or_b32_e32 v24, s53, v2
	s_add_i32 s13, s13, 16
	s_add_i32 s12, s12, 16
	s_add_i32 s51, s51, -16
	v_mad_u64_u32 v[24:25], s[52:53], v24, s16, v[8:9]
	v_mad_u64_u32 v[28:29], s[52:53], v28, s16, v[8:9]
	v_or_b32_e32 v25, s60, v1
	v_or_b32_e32 v29, s61, v2
	v_or_b32_e32 v36, s62, v1
	v_or_b32_e32 v34, s63, v2
	v_or_b32_e32 v40, s64, v1
	v_or_b32_e32 v38, s65, v2
	v_or_b32_e32 v44, s66, v1
	v_or_b32_e32 v42, s67, v2
	v_or_b32_e32 v48, s68, v1
	v_or_b32_e32 v46, s69, v2
	v_or_b32_e32 v52, s70, v1
	v_or_b32_e32 v50, s71, v2
	v_or_b32_e32 v56, s72, v1
	v_or_b32_e32 v54, s73, v2
	s_cmp_lg_u32 s51, 0
	v_mad_u64_u32 v[30:31], s[52:53], v29, s16, v[8:9]
	v_mad_u64_u32 v[32:33], s[52:53], v25, s16, v[8:9]
	v_mad_u64_u32 v[34:35], s[52:53], v34, s16, v[8:9]
	v_mad_u64_u32 v[36:37], s[52:53], v36, s16, v[8:9]
	v_mad_u64_u32 v[38:39], s[52:53], v38, s16, v[8:9]
	v_mad_u64_u32 v[40:41], s[52:53], v40, s16, v[8:9]
	v_mad_u64_u32 v[42:43], s[52:53], v42, s16, v[8:9]
	v_mad_u64_u32 v[44:45], s[52:53], v44, s16, v[8:9]
	v_mad_u64_u32 v[46:47], s[52:53], v46, s16, v[8:9]
	v_mad_u64_u32 v[48:49], s[52:53], v48, s16, v[8:9]
	v_mad_u64_u32 v[50:51], s[52:53], v50, s16, v[8:9]
	v_mad_u64_u32 v[52:53], s[52:53], v52, s16, v[8:9]
	v_mad_u64_u32 v[54:55], s[52:53], v54, s16, v[8:9]
	v_mad_u64_u32 v[56:57], s[52:53], v56, s16, v[8:9]
	s_waitcnt vmcnt(15)
	ds_write_b32 v24, v11
	s_waitcnt vmcnt(14)
	ds_write_b32 v28, v13
	s_waitcnt vmcnt(13)
	ds_write_b32 v30, v58
	s_waitcnt vmcnt(12)
	ds_write_b32 v32, v59
	s_waitcnt vmcnt(11)
	ds_write_b32 v34, v60
	s_waitcnt vmcnt(10)
	ds_write_b32 v36, v61
	s_waitcnt vmcnt(9)
	ds_write_b32 v38, v62
	s_waitcnt vmcnt(8)
	ds_write_b32 v40, v63
	s_waitcnt vmcnt(7)
	ds_write_b32 v42, v64
	s_waitcnt vmcnt(6)
	ds_write_b32 v44, v65
	s_waitcnt vmcnt(5)
	ds_write_b32 v46, v66
	s_waitcnt vmcnt(4)
	ds_write_b32 v48, v67
	s_waitcnt vmcnt(3)
	ds_write_b32 v50, v6
	s_waitcnt vmcnt(2)
	ds_write_b32 v52, v68
	s_waitcnt vmcnt(1)
	ds_write_b32 v54, v69
	s_waitcnt vmcnt(0)
	ds_write_b32 v56, v70
	s_cbranch_scc1 .LBB0_26
	s_lshl_b64 s[8:9], s[8:9], 1
	s_waitcnt lgkmcnt(0)
	s_add_u32 s8, s14, s8
	ds_read2_b32 v[14:15], v23 offset0:33 offset1:41
	ds_read2_b32 v[24:25], v23 offset1:8
	ds_read2_b32 v[32:33], v23 offset0:66 offset1:74
	ds_read2_b32 v[34:35], v23 offset0:99 offset1:107
	ds_read2_b32 v[36:37], v23 offset0:132 offset1:140
	ds_read2_b32 v[38:39], v23 offset0:165 offset1:173
	ds_read2_b32 v[40:41], v23 offset0:198 offset1:206
	ds_read2_b32 v[42:43], v23 offset0:231 offset1:239
	s_addc_u32 s9, s15, s9
	s_lshl_b32 s11, s11, 1
	s_add_u32 s8, s8, s11
	s_addc_u32 s9, s9, 0
	v_mov_b32_e32 v13, v7
	v_or_b32_e32 v3, s6, v5
	v_lshl_add_u64 v[44:45], s[8:9], 0, v[12:13]
	v_lshlrev_b32_e32 v6, 13, v3
	s_waitcnt lgkmcnt(6)
	v_cvt_pk_bf16_f32 v28, v24, v14
	s_waitcnt lgkmcnt(4)
	v_cvt_pk_bf16_f32 v29, v32, v34
	s_waitcnt lgkmcnt(2)
	v_cvt_pk_bf16_f32 v30, v36, v38
	s_waitcnt lgkmcnt(0)
	v_cvt_pk_bf16_f32 v31, v40, v42
	v_lshl_add_u64 v[46:47], v[44:45], 0, v[6:7]
	global_store_dwordx4 v[46:47], v[28:31], off
	v_or_b32_e32 v3, s6, v9
	v_lshlrev_b32_e32 v6, 13, v3
	v_cvt_pk_bf16_f32 v28, v25, v15
	v_cvt_pk_bf16_f32 v29, v33, v35
	v_cvt_pk_bf16_f32 v30, v37, v39
	v_cvt_pk_bf16_f32 v31, v41, v43
	ds_read2_b32 v[24:25], v23 offset0:49 offset1:57
	ds_read2_b32 v[32:33], v23 offset0:16 offset1:24
	ds_read2_b32 v[34:35], v23 offset0:82 offset1:90
	ds_read2_b32 v[36:37], v23 offset0:115 offset1:123
	ds_read2_b32 v[38:39], v23 offset0:148 offset1:156
	ds_read2_b32 v[40:41], v23 offset0:181 offset1:189
	ds_read2_b32 v[42:43], v23 offset0:214 offset1:222
	ds_read2_b32 v[46:47], v23 offset0:247 offset1:255
	v_or_b32_e32 v3, s6, v17
	v_lshl_add_u64 v[14:15], v[44:45], 0, v[6:7]
	v_lshlrev_b32_e32 v6, 13, v3
	v_or_b32_e32 v3, s6, v18
	global_store_dwordx4 v[14:15], v[28:31], off
	v_lshl_add_u64 v[14:15], v[44:45], 0, v[6:7]
	v_lshlrev_b32_e32 v6, 13, v3
	s_waitcnt lgkmcnt(6)
	v_cvt_pk_bf16_f32 v28, v32, v24
	s_waitcnt lgkmcnt(4)
	v_cvt_pk_bf16_f32 v29, v34, v36
	s_waitcnt lgkmcnt(2)
	v_cvt_pk_bf16_f32 v30, v38, v40
	s_waitcnt lgkmcnt(0)
	v_cvt_pk_bf16_f32 v31, v42, v46
	global_store_dwordx4 v[14:15], v[28:31], off
	v_lshl_add_u64 v[14:15], v[44:45], 0, v[6:7]
	s_mov_b64 s[8:9], 0
	v_cvt_pk_bf16_f32 v28, v33, v25
	v_cvt_pk_bf16_f32 v29, v35, v37
	v_cvt_pk_bf16_f32 v30, v39, v41
	v_cvt_pk_bf16_f32 v31, v43, v47
	global_store_dwordx4 v[14:15], v[28:31], off
	s_waitcnt lgkmcnt(0)

.LBB0_30:
	s_lshl_b32 s51, s11, 1
	s_lshl_b32 s52, s10, 1
	v_or_b32_e32 v6, s52, v16
	s_add_i32 s60, s51, 4
	s_add_i32 s61, s52, 4
	v_mov_b32_e32 v29, v7
	s_add_i32 s63, s52, 8
	v_lshlrev_b64 v[42:43], 14, v[6:7]
	v_or_b32_e32 v28, s60, v3
	v_or_b32_e32 v6, s61, v16
	v_mov_b32_e32 v25, v7
	v_or_b32_e32 v24, s51, v3
	s_add_i32 s65, s52, 12
	v_lshlrev_b64 v[28:29], 14, v[28:29]
	v_lshlrev_b64 v[44:45], 14, v[6:7]
	v_or_b32_e32 v6, s63, v16
	s_add_i32 s62, s51, 8
	s_add_i32 s64, s51, 12
	s_add_i32 s67, s52, 16
	v_lshlrev_b64 v[24:25], 14, v[24:25]
	v_lshl_add_u64 v[42:43], v[14:15], 0, v[42:43]
	v_lshl_add_u64 v[28:29], v[14:15], 0, v[28:29]
	v_lshlrev_b64 v[46:47], 14, v[6:7]
	v_or_b32_e32 v6, s65, v16
	v_mov_b32_e32 v31, v7
	v_mov_b32_e32 v33, v7
	s_add_i32 s69, s52, 20
	v_or_b32_e32 v30, s62, v3
	v_or_b32_e32 v32, s64, v3
	v_lshl_add_u64 v[24:25], v[14:15], 0, v[24:25]
	v_lshl_add_u64 v[44:45], v[14:15], 0, v[44:45]
	global_load_dword v11, v[42:43], off nt
	global_load_dword v13, v[24:25], off nt
	global_load_dword v58, v[44:45], off nt
	global_load_dword v59, v[28:29], off nt
	v_lshlrev_b64 v[28:29], 14, v[6:7]
	v_or_b32_e32 v6, s67, v16
	s_add_i32 s66, s51, 16
	s_add_i32 s68, s51, 20
	s_add_i32 s71, s52, 24
	v_lshlrev_b64 v[30:31], 14, v[30:31]
	v_lshlrev_b64 v[32:33], 14, v[32:33]
	v_lshl_add_u64 v[24:25], v[14:15], 0, v[46:47]
	v_lshl_add_u64 v[28:29], v[14:15], 0, v[28:29]
	v_lshlrev_b64 v[42:43], 14, v[6:7]
	v_or_b32_e32 v6, s69, v16
	v_mov_b32_e32 v35, v7
	v_mov_b32_e32 v37, v7
	s_add_i32 s70, s51, 24
	s_add_i32 s72, s51, 28
	s_add_i32 s73, s52, 28
	v_or_b32_e32 v34, s66, v3
	v_or_b32_e32 v36, s68, v3
	v_lshl_add_u64 v[30:31], v[14:15], 0, v[30:31]
	v_lshl_add_u64 v[32:33], v[14:15], 0, v[32:33]
	global_load_dword v60, v[24:25], off nt
	global_load_dword v61, v[30:31], off nt
	global_load_dword v62, v[28:29], off nt
	global_load_dword v63, v[32:33], off nt
	v_lshlrev_b64 v[28:29], 14, v[6:7]
	v_or_b32_e32 v6, s71, v16
	v_mov_b32_e32 v39, v7
	v_mov_b32_e32 v41, v7
	v_or_b32_e32 v38, s70, v3
	v_or_b32_e32 v40, s72, v3
	v_lshlrev_b64 v[34:35], 14, v[34:35]
	v_lshlrev_b64 v[36:37], 14, v[36:37]
	v_lshl_add_u64 v[24:25], v[14:15], 0, v[42:43]
	v_lshl_add_u64 v[28:29], v[14:15], 0, v[28:29]
	v_lshlrev_b64 v[30:31], 14, v[6:7]
	v_or_b32_e32 v6, s73, v16
	v_lshlrev_b64 v[38:39], 14, v[38:39]
	v_lshlrev_b64 v[40:41], 14, v[40:41]
	v_lshl_add_u64 v[34:35], v[14:15], 0, v[34:35]
	v_lshl_add_u64 v[36:37], v[14:15], 0, v[36:37]
	global_load_dword v64, v[24:25], off nt
	global_load_dword v65, v[34:35], off nt
	global_load_dword v66, v[28:29], off nt
	global_load_dword v67, v[36:37], off nt
	v_lshl_add_u64 v[24:25], v[14:15], 0, v[30:31]
	v_lshlrev_b64 v[28:29], 14, v[6:7]
	v_lshl_add_u64 v[38:39], v[14:15], 0, v[38:39]
	v_lshl_add_u64 v[40:41], v[14:15], 0, v[40:41]
	v_lshl_add_u64 v[28:29], v[14:15], 0, v[28:29]
	global_load_dword v6, v[24:25], off nt
	global_load_dword v68, v[38:39], off nt
	global_load_dword v69, v[28:29], off nt
	global_load_dword v70, v[40:41], off nt
	v_or_b32_e32 v28, s51, v1
	v_or_b32_e32 v24, s52, v2
	s_add_i32 s10, s10, 16
	s_add_i32 s11, s11, 16
	s_add_i32 s13, s13, -16
	v_mad_u64_u32 v[24:25], s[52:53], v24, s16, v[8:9]
	v_mad_u64_u32 v[28:29], s[52:53], v28, s16, v[8:9]
	v_or_b32_e32 v25, s60, v1
	v_or_b32_e32 v29, s61, v2
	v_or_b32_e32 v36, s62, v1
	v_or_b32_e32 v34, s63, v2
	v_or_b32_e32 v40, s64, v1
	v_or_b32_e32 v38, s65, v2
	v_or_b32_e32 v44, s66, v1
	v_or_b32_e32 v42, s67, v2
	v_or_b32_e32 v48, s68, v1
	v_or_b32_e32 v46, s69, v2
	v_or_b32_e32 v52, s70, v1
	v_or_b32_e32 v50, s71, v2
	v_or_b32_e32 v56, s72, v1
	v_or_b32_e32 v54, s73, v2
	s_cmp_lg_u32 s13, 0
	v_mad_u64_u32 v[30:31], s[52:53], v29, s16, v[8:9]
	v_mad_u64_u32 v[32:33], s[52:53], v25, s16, v[8:9]
	v_mad_u64_u32 v[34:35], s[52:53], v34, s16, v[8:9]
	v_mad_u64_u32 v[36:37], s[52:53], v36, s16, v[8:9]
	v_mad_u64_u32 v[38:39], s[52:53], v38, s16, v[8:9]
	v_mad_u64_u32 v[40:41], s[52:53], v40, s16, v[8:9]
	v_mad_u64_u32 v[42:43], s[52:53], v42, s16, v[8:9]
	v_mad_u64_u32 v[44:45], s[52:53], v44, s16, v[8:9]
	v_mad_u64_u32 v[46:47], s[52:53], v46, s16, v[8:9]
	v_mad_u64_u32 v[48:49], s[52:53], v48, s16, v[8:9]
	v_mad_u64_u32 v[50:51], s[52:53], v50, s16, v[8:9]
	v_mad_u64_u32 v[52:53], s[52:53], v52, s16, v[8:9]
	v_mad_u64_u32 v[54:55], s[52:53], v54, s16, v[8:9]
	v_mad_u64_u32 v[56:57], s[52:53], v56, s16, v[8:9]
	s_waitcnt vmcnt(15)
	ds_write_b32 v24, v11
	s_waitcnt vmcnt(14)
	ds_write_b32 v28, v13
	s_waitcnt vmcnt(13)
	ds_write_b32 v30, v58
	s_waitcnt vmcnt(12)
	ds_write_b32 v32, v59
	s_waitcnt vmcnt(11)
	ds_write_b32 v34, v60
	s_waitcnt vmcnt(10)
	ds_write_b32 v36, v61
	s_waitcnt vmcnt(9)
	ds_write_b32 v38, v62
	s_waitcnt vmcnt(8)
	ds_write_b32 v40, v63
	s_waitcnt vmcnt(7)
	ds_write_b32 v42, v64
	s_waitcnt vmcnt(6)
	ds_write_b32 v44, v65
	s_waitcnt vmcnt(5)
	ds_write_b32 v46, v66
	s_waitcnt vmcnt(4)
	ds_write_b32 v48, v67
	s_waitcnt vmcnt(3)
	ds_write_b32 v50, v6
	s_waitcnt vmcnt(2)
	ds_write_b32 v52, v68
	s_waitcnt vmcnt(1)
	ds_write_b32 v54, v69
	s_waitcnt vmcnt(0)
	ds_write_b32 v56, v70
	s_cbranch_scc1 .LBB0_30
	s_lshl_b64 s[8:9], s[8:9], 1
	s_waitcnt lgkmcnt(0)
	s_add_u32 s8, s17, s8
	ds_read2_b32 v[14:15], v23 offset0:33 offset1:41
	ds_read2_b32 v[24:25], v23 offset1:8
	ds_read2_b32 v[32:33], v23 offset0:66 offset1:74
	ds_read2_b32 v[34:35], v23 offset0:99 offset1:107
	ds_read2_b32 v[36:37], v23 offset0:132 offset1:140
	ds_read2_b32 v[38:39], v23 offset0:165 offset1:173
	ds_read2_b32 v[40:41], v23 offset0:198 offset1:206
	ds_read2_b32 v[42:43], v23 offset0:231 offset1:239
	s_addc_u32 s9, s18, s9
	s_lshl_b32 s10, s12, 1
	s_add_u32 s8, s8, s10
	s_addc_u32 s9, s9, 0
	v_mov_b32_e32 v13, v7
	v_or_b32_e32 v3, s6, v5
	v_lshl_add_u64 v[44:45], s[8:9], 0, v[12:13]
	v_lshlrev_b32_e32 v6, 11, v3
	s_waitcnt lgkmcnt(6)
	v_cvt_pk_bf16_f32 v28, v24, v14
	s_waitcnt lgkmcnt(4)
	v_cvt_pk_bf16_f32 v29, v32, v34
	s_waitcnt lgkmcnt(2)
	v_cvt_pk_bf16_f32 v30, v36, v38
	s_waitcnt lgkmcnt(0)
	v_cvt_pk_bf16_f32 v31, v40, v42
	v_lshl_add_u64 v[46:47], v[44:45], 0, v[6:7]
	global_store_dwordx4 v[46:47], v[28:31], off
	v_or_b32_e32 v3, s6, v9
	v_lshlrev_b32_e32 v6, 11, v3
	v_cvt_pk_bf16_f32 v28, v25, v15
	v_cvt_pk_bf16_f32 v29, v33, v35
	v_cvt_pk_bf16_f32 v30, v37, v39
	v_cvt_pk_bf16_f32 v31, v41, v43
	ds_read2_b32 v[24:25], v23 offset0:49 offset1:57
	ds_read2_b32 v[32:33], v23 offset0:16 offset1:24
	ds_read2_b32 v[34:35], v23 offset0:82 offset1:90
	ds_read2_b32 v[36:37], v23 offset0:115 offset1:123
	ds_read2_b32 v[38:39], v23 offset0:148 offset1:156
	ds_read2_b32 v[40:41], v23 offset0:181 offset1:189
	ds_read2_b32 v[42:43], v23 offset0:214 offset1:222
	ds_read2_b32 v[46:47], v23 offset0:247 offset1:255
	v_or_b32_e32 v3, s6, v17
	v_lshl_add_u64 v[14:15], v[44:45], 0, v[6:7]
	v_lshlrev_b32_e32 v6, 11, v3
	v_or_b32_e32 v3, s6, v18
	global_store_dwordx4 v[14:15], v[28:31], off
	v_lshl_add_u64 v[14:15], v[44:45], 0, v[6:7]
	v_lshlrev_b32_e32 v6, 11, v3
	s_waitcnt lgkmcnt(6)
	v_cvt_pk_bf16_f32 v28, v32, v24
	s_waitcnt lgkmcnt(4)
	v_cvt_pk_bf16_f32 v29, v34, v36
	s_waitcnt lgkmcnt(2)
	v_cvt_pk_bf16_f32 v30, v38, v40
	s_waitcnt lgkmcnt(0)
	v_cvt_pk_bf16_f32 v31, v42, v46
	global_store_dwordx4 v[14:15], v[28:31], off
	v_lshl_add_u64 v[14:15], v[44:45], 0, v[6:7]
	s_nop 0
	v_cvt_pk_bf16_f32 v28, v33, v25
	v_cvt_pk_bf16_f32 v29, v35, v37
	v_cvt_pk_bf16_f32 v30, v39, v41
	v_cvt_pk_bf16_f32 v31, v43, v47
	global_store_dwordx4 v[14:15], v[28:31], off
	s_waitcnt lgkmcnt(0)

.LBB0_35:
	s_lshl_b32 s51, s11, 1
	s_lshl_b32 s52, s12, 1
	v_or_b32_e32 v6, s52, v16
	s_add_i32 s60, s51, 4
	s_add_i32 s61, s52, 4
	v_mov_b32_e32 v29, v7
	s_add_i32 s63, s52, 8
	v_lshlrev_b64 v[42:43], 12, v[6:7]
	v_or_b32_e32 v28, s60, v3
	v_or_b32_e32 v6, s61, v16
	v_mov_b32_e32 v25, v7
	v_or_b32_e32 v24, s51, v3
	s_add_i32 s65, s52, 12
	v_lshlrev_b64 v[28:29], 12, v[28:29]
	v_lshlrev_b64 v[44:45], 12, v[6:7]
	v_or_b32_e32 v6, s63, v16
	s_add_i32 s62, s51, 8
	s_add_i32 s64, s51, 12
	s_add_i32 s67, s52, 16
	v_lshlrev_b64 v[24:25], 12, v[24:25]
	v_lshl_add_u64 v[42:43], v[14:15], 0, v[42:43]
	v_lshl_add_u64 v[28:29], v[14:15], 0, v[28:29]
	v_lshlrev_b64 v[46:47], 12, v[6:7]
	v_or_b32_e32 v6, s65, v16
	v_mov_b32_e32 v31, v7
	v_mov_b32_e32 v33, v7
	s_add_i32 s69, s52, 20
	v_or_b32_e32 v30, s62, v3
	v_or_b32_e32 v32, s64, v3
	v_lshl_add_u64 v[24:25], v[14:15], 0, v[24:25]
	v_lshl_add_u64 v[44:45], v[14:15], 0, v[44:45]
	global_load_dword v11, v[42:43], off nt
	global_load_dword v13, v[24:25], off nt
	global_load_dword v58, v[44:45], off nt
	global_load_dword v59, v[28:29], off nt
	v_lshlrev_b64 v[28:29], 12, v[6:7]
	v_or_b32_e32 v6, s67, v16
	s_add_i32 s66, s51, 16
	s_add_i32 s68, s51, 20
	s_add_i32 s71, s52, 24
	v_lshlrev_b64 v[30:31], 12, v[30:31]
	v_lshlrev_b64 v[32:33], 12, v[32:33]
	v_lshl_add_u64 v[24:25], v[14:15], 0, v[46:47]
	v_lshl_add_u64 v[28:29], v[14:15], 0, v[28:29]
	v_lshlrev_b64 v[42:43], 12, v[6:7]
	v_or_b32_e32 v6, s69, v16
	v_mov_b32_e32 v35, v7
	v_mov_b32_e32 v37, v7
	s_add_i32 s70, s51, 24
	s_add_i32 s72, s51, 28
	s_add_i32 s73, s52, 28
	v_or_b32_e32 v34, s66, v3
	v_or_b32_e32 v36, s68, v3
	v_lshl_add_u64 v[30:31], v[14:15], 0, v[30:31]
	v_lshl_add_u64 v[32:33], v[14:15], 0, v[32:33]
	global_load_dword v60, v[24:25], off nt
	global_load_dword v61, v[30:31], off nt
	global_load_dword v62, v[28:29], off nt
	global_load_dword v63, v[32:33], off nt
	v_lshlrev_b64 v[28:29], 12, v[6:7]
	v_or_b32_e32 v6, s71, v16
	v_mov_b32_e32 v39, v7
	v_mov_b32_e32 v41, v7
	v_or_b32_e32 v38, s70, v3
	v_or_b32_e32 v40, s72, v3
	v_lshlrev_b64 v[34:35], 12, v[34:35]
	v_lshlrev_b64 v[36:37], 12, v[36:37]
	v_lshl_add_u64 v[24:25], v[14:15], 0, v[42:43]
	v_lshl_add_u64 v[28:29], v[14:15], 0, v[28:29]
	v_lshlrev_b64 v[30:31], 12, v[6:7]
	v_or_b32_e32 v6, s73, v16
	v_lshlrev_b64 v[38:39], 12, v[38:39]
	v_lshlrev_b64 v[40:41], 12, v[40:41]
	v_lshl_add_u64 v[34:35], v[14:15], 0, v[34:35]
	v_lshl_add_u64 v[36:37], v[14:15], 0, v[36:37]
	global_load_dword v64, v[24:25], off nt
	global_load_dword v65, v[34:35], off nt
	global_load_dword v66, v[28:29], off nt
	global_load_dword v67, v[36:37], off nt
	v_lshl_add_u64 v[24:25], v[14:15], 0, v[30:31]
	v_lshlrev_b64 v[28:29], 12, v[6:7]
	v_lshl_add_u64 v[38:39], v[14:15], 0, v[38:39]
	v_lshl_add_u64 v[40:41], v[14:15], 0, v[40:41]
	v_lshl_add_u64 v[28:29], v[14:15], 0, v[28:29]
	global_load_dword v6, v[24:25], off nt
	global_load_dword v68, v[38:39], off nt
	global_load_dword v69, v[28:29], off nt
	global_load_dword v70, v[40:41], off nt
	v_or_b32_e32 v28, s51, v1
	v_or_b32_e32 v24, s52, v2
	s_add_i32 s12, s12, 16
	s_add_i32 s11, s11, 16
	s_add_i32 s13, s13, -16
	v_mad_u64_u32 v[24:25], s[52:53], v24, s16, v[8:9]
	v_mad_u64_u32 v[28:29], s[52:53], v28, s16, v[8:9]
	v_or_b32_e32 v25, s60, v1
	v_or_b32_e32 v29, s61, v2
	v_or_b32_e32 v36, s62, v1
	v_or_b32_e32 v34, s63, v2
	v_or_b32_e32 v40, s64, v1
	v_or_b32_e32 v38, s65, v2
	v_or_b32_e32 v44, s66, v1
	v_or_b32_e32 v42, s67, v2
	v_or_b32_e32 v48, s68, v1
	v_or_b32_e32 v46, s69, v2
	v_or_b32_e32 v52, s70, v1
	v_or_b32_e32 v50, s71, v2
	v_or_b32_e32 v56, s72, v1
	v_or_b32_e32 v54, s73, v2
	s_cmp_lg_u32 s13, 0
	v_mad_u64_u32 v[30:31], s[52:53], v29, s16, v[8:9]
	v_mad_u64_u32 v[32:33], s[52:53], v25, s16, v[8:9]
	v_mad_u64_u32 v[34:35], s[52:53], v34, s16, v[8:9]
	v_mad_u64_u32 v[36:37], s[52:53], v36, s16, v[8:9]
	v_mad_u64_u32 v[38:39], s[52:53], v38, s16, v[8:9]
	v_mad_u64_u32 v[40:41], s[52:53], v40, s16, v[8:9]
	v_mad_u64_u32 v[42:43], s[52:53], v42, s16, v[8:9]
	v_mad_u64_u32 v[44:45], s[52:53], v44, s16, v[8:9]
	v_mad_u64_u32 v[46:47], s[52:53], v46, s16, v[8:9]
	v_mad_u64_u32 v[48:49], s[52:53], v48, s16, v[8:9]
	v_mad_u64_u32 v[50:51], s[52:53], v50, s16, v[8:9]
	v_mad_u64_u32 v[52:53], s[52:53], v52, s16, v[8:9]
	v_mad_u64_u32 v[54:55], s[52:53], v54, s16, v[8:9]
	v_mad_u64_u32 v[56:57], s[52:53], v56, s16, v[8:9]
	s_waitcnt vmcnt(15)
	ds_write_b32 v24, v11
	s_waitcnt vmcnt(14)
	ds_write_b32 v28, v13
	s_waitcnt vmcnt(13)
	ds_write_b32 v30, v58
	s_waitcnt vmcnt(12)
	ds_write_b32 v32, v59
	s_waitcnt vmcnt(11)
	ds_write_b32 v34, v60
	s_waitcnt vmcnt(10)
	ds_write_b32 v36, v61
	s_waitcnt vmcnt(9)
	ds_write_b32 v38, v62
	s_waitcnt vmcnt(8)
	ds_write_b32 v40, v63
	s_waitcnt vmcnt(7)
	ds_write_b32 v42, v64
	s_waitcnt vmcnt(6)
	ds_write_b32 v44, v65
	s_waitcnt vmcnt(5)
	ds_write_b32 v46, v66
	s_waitcnt vmcnt(4)
	ds_write_b32 v48, v67
	s_waitcnt vmcnt(3)
	ds_write_b32 v50, v6
	s_waitcnt vmcnt(2)
	ds_write_b32 v52, v68
	s_waitcnt vmcnt(1)
	ds_write_b32 v54, v69
	s_waitcnt vmcnt(0)
	ds_write_b32 v56, v70
	s_cbranch_scc1 .LBB0_35
	s_lshl_b64 s[8:9], s[8:9], 1
	s_waitcnt lgkmcnt(0)
	s_add_u32 s8, s19, s8
	ds_read2_b32 v[14:15], v23 offset0:33 offset1:41
	ds_read2_b32 v[24:25], v23 offset1:8
	ds_read2_b32 v[32:33], v23 offset0:66 offset1:74
	ds_read2_b32 v[34:35], v23 offset0:99 offset1:107
	ds_read2_b32 v[36:37], v23 offset0:132 offset1:140
	ds_read2_b32 v[38:39], v23 offset0:165 offset1:173
	ds_read2_b32 v[40:41], v23 offset0:198 offset1:206
	ds_read2_b32 v[42:43], v23 offset0:231 offset1:239
	s_addc_u32 s9, s20, s9
	s_lshl_b32 s10, s10, 1
	s_add_u32 s8, s8, s10
	s_addc_u32 s9, s9, 0
	v_mov_b32_e32 v13, v7
	v_or_b32_e32 v3, s6, v5
	v_lshl_add_u64 v[44:45], s[8:9], 0, v[12:13]
	v_lshlrev_b32_e32 v6, 12, v3
	s_waitcnt lgkmcnt(6)
	v_cvt_pk_bf16_f32 v28, v24, v14
	s_waitcnt lgkmcnt(4)
	v_cvt_pk_bf16_f32 v29, v32, v34
	s_waitcnt lgkmcnt(2)
	v_cvt_pk_bf16_f32 v30, v36, v38
	s_waitcnt lgkmcnt(0)
	v_cvt_pk_bf16_f32 v31, v40, v42
	v_lshl_add_u64 v[46:47], v[44:45], 0, v[6:7]
	global_store_dwordx4 v[46:47], v[28:31], off
	v_or_b32_e32 v3, s6, v9
	v_lshlrev_b32_e32 v6, 12, v3
	v_cvt_pk_bf16_f32 v28, v25, v15
	v_cvt_pk_bf16_f32 v29, v33, v35
	v_cvt_pk_bf16_f32 v30, v37, v39
	v_cvt_pk_bf16_f32 v31, v41, v43
	ds_read2_b32 v[24:25], v23 offset0:49 offset1:57
	ds_read2_b32 v[32:33], v23 offset0:16 offset1:24
	ds_read2_b32 v[34:35], v23 offset0:82 offset1:90
	ds_read2_b32 v[36:37], v23 offset0:115 offset1:123
	ds_read2_b32 v[38:39], v23 offset0:148 offset1:156
	ds_read2_b32 v[40:41], v23 offset0:181 offset1:189
	ds_read2_b32 v[42:43], v23 offset0:214 offset1:222
	ds_read2_b32 v[46:47], v23 offset0:247 offset1:255
	v_or_b32_e32 v3, s6, v17
	v_lshl_add_u64 v[14:15], v[44:45], 0, v[6:7]
	v_lshlrev_b32_e32 v6, 12, v3
	v_or_b32_e32 v3, s6, v18
	global_store_dwordx4 v[14:15], v[28:31], off
	v_lshl_add_u64 v[14:15], v[44:45], 0, v[6:7]
	v_lshlrev_b32_e32 v6, 12, v3
	s_waitcnt lgkmcnt(6)
	v_cvt_pk_bf16_f32 v28, v32, v24
	s_waitcnt lgkmcnt(4)
	v_cvt_pk_bf16_f32 v29, v34, v36
	s_waitcnt lgkmcnt(2)
	v_cvt_pk_bf16_f32 v30, v38, v40
	s_waitcnt lgkmcnt(0)
	v_cvt_pk_bf16_f32 v31, v42, v46
	global_store_dwordx4 v[14:15], v[28:31], off
	v_lshl_add_u64 v[14:15], v[44:45], 0, v[6:7]
	s_nop 0
	v_cvt_pk_bf16_f32 v28, v33, v25
	v_cvt_pk_bf16_f32 v29, v35, v37
	v_cvt_pk_bf16_f32 v30, v39, v41
	v_cvt_pk_bf16_f32 v31, v43, v47
	global_store_dwordx4 v[14:15], v[28:31], off
	s_waitcnt lgkmcnt(0)

.LBB0_40:
	s_lshl_b32 s60, s52, 1
	s_lshl_b32 s61, s12, 1
	v_or_b32_e32 v3, s60, v1
	v_or_b32_e32 v11, s61, v2
	s_add_i32 s62, s60, 4
	s_add_i32 s63, s61, 4
	s_add_i32 s64, s60, 8
	s_add_i32 s65, s61, 8
	s_add_i32 s66, s60, 12
	s_add_i32 s67, s61, 12
	s_add_i32 s68, s60, 16
	s_add_i32 s69, s61, 16
	s_add_i32 s70, s60, 20
	s_add_i32 s71, s61, 20
	s_add_i32 s72, s60, 24
	s_add_i32 s73, s61, 24
	s_add_i32 s60, s60, 28
	s_add_i32 s61, s61, 28
	v_add_u32_e32 v13, s13, v11
	v_or_b32_e32 v16, s62, v1
	v_or_b32_e32 v56, s63, v2
	v_or_b32_e32 v57, s64, v1
	v_or_b32_e32 v58, s65, v2
	v_or_b32_e32 v59, s66, v1
	v_or_b32_e32 v60, s67, v2
	v_or_b32_e32 v61, s68, v1
	v_or_b32_e32 v62, s69, v2
	v_or_b32_e32 v63, s70, v1
	v_or_b32_e32 v64, s71, v2
	v_or_b32_e32 v65, s72, v1
	v_or_b32_e32 v66, s73, v2
	v_or_b32_e32 v67, s60, v1
	v_or_b32_e32 v68, s61, v2
	v_add_u32_e32 v14, s51, v3
	v_mad_u64_u32 v[24:25], s[60:61], v13, s47, v[6:7]
	v_add_u32_e32 v13, s13, v56
	v_add_u32_e32 v28, s51, v16
	v_add_u32_e32 v34, s13, v58
	v_add_u32_e32 v32, s51, v57
	v_add_u32_e32 v38, s13, v60
	v_add_u32_e32 v36, s51, v59
	v_add_u32_e32 v42, s13, v62
	v_add_u32_e32 v40, s51, v61
	v_add_u32_e32 v46, s13, v64
	v_add_u32_e32 v44, s51, v63
	v_add_u32_e32 v50, s13, v66
	v_add_u32_e32 v48, s51, v65
	v_add_u32_e32 v54, s13, v68
	v_add_u32_e32 v52, s51, v67
	v_mad_u64_u32 v[14:15], s[60:61], v14, s47, v[6:7]
	v_mov_b32_e32 v25, v7
	v_mad_u64_u32 v[28:29], s[60:61], v28, s47, v[6:7]
	v_mad_u64_u32 v[30:31], s[60:61], v13, s47, v[6:7]
	v_mad_u64_u32 v[32:33], s[60:61], v32, s47, v[6:7]
	v_mad_u64_u32 v[34:35], s[60:61], v34, s47, v[6:7]
	v_mad_u64_u32 v[36:37], s[60:61], v36, s47, v[6:7]
	v_mad_u64_u32 v[38:39], s[60:61], v38, s47, v[6:7]
	v_mad_u64_u32 v[40:41], s[60:61], v40, s47, v[6:7]
	v_mad_u64_u32 v[42:43], s[60:61], v42, s47, v[6:7]
	v_mad_u64_u32 v[44:45], s[60:61], v44, s47, v[6:7]
	v_mad_u64_u32 v[46:47], s[60:61], v46, s47, v[6:7]
	v_mad_u64_u32 v[48:49], s[60:61], v48, s47, v[6:7]
	v_mad_u64_u32 v[50:51], s[60:61], v50, s47, v[6:7]
	v_mad_u64_u32 v[52:53], s[60:61], v52, s47, v[6:7]
	v_mad_u64_u32 v[54:55], s[60:61], v54, s47, v[6:7]
	v_mov_b32_e32 v15, v7
	v_lshl_add_u64 v[24:25], v[24:25], 2, s[8:9]
	v_mov_b32_e32 v31, v7
	v_mov_b32_e32 v29, v7
	v_mov_b32_e32 v35, v7
	v_mov_b32_e32 v33, v7
	v_mov_b32_e32 v39, v7
	v_mov_b32_e32 v37, v7
	v_mov_b32_e32 v43, v7
	v_mov_b32_e32 v41, v7
	v_mov_b32_e32 v47, v7
	v_mov_b32_e32 v45, v7
	v_mov_b32_e32 v51, v7
	v_mov_b32_e32 v49, v7
	v_mov_b32_e32 v55, v7
	v_mov_b32_e32 v53, v7
	v_lshl_add_u64 v[14:15], v[14:15], 2, s[8:9]
	v_lshl_add_u64 v[30:31], v[30:31], 2, s[8:9]
	v_lshl_add_u64 v[28:29], v[28:29], 2, s[8:9]
	v_lshl_add_u64 v[34:35], v[34:35], 2, s[8:9]
	v_lshl_add_u64 v[32:33], v[32:33], 2, s[8:9]
	v_lshl_add_u64 v[38:39], v[38:39], 2, s[8:9]
	v_lshl_add_u64 v[36:37], v[36:37], 2, s[8:9]
	v_lshl_add_u64 v[42:43], v[42:43], 2, s[8:9]
	v_lshl_add_u64 v[40:41], v[40:41], 2, s[8:9]
	v_lshl_add_u64 v[46:47], v[46:47], 2, s[8:9]
	v_lshl_add_u64 v[44:45], v[44:45], 2, s[8:9]
	v_lshl_add_u64 v[50:51], v[50:51], 2, s[8:9]
	v_lshl_add_u64 v[48:49], v[48:49], 2, s[8:9]
	v_lshl_add_u64 v[54:55], v[54:55], 2, s[8:9]
	v_lshl_add_u64 v[52:53], v[52:53], 2, s[8:9]
	global_load_dword v13, v[24:25], off nt
	global_load_dword v69, v[14:15], off nt
	global_load_dword v70, v[30:31], off nt
	global_load_dword v71, v[28:29], off nt
	global_load_dword v72, v[34:35], off nt
	global_load_dword v73, v[32:33], off nt
	global_load_dword v74, v[38:39], off nt
	global_load_dword v75, v[36:37], off nt
	global_load_dword v76, v[42:43], off nt
	global_load_dword v77, v[40:41], off nt
	global_load_dword v78, v[46:47], off nt
	global_load_dword v79, v[44:45], off nt
	global_load_dword v80, v[50:51], off nt
	global_load_dword v81, v[48:49], off nt
	global_load_dword v82, v[54:55], off nt
	global_load_dword v83, v[52:53], off nt
	s_add_i32 s12, s12, 16
	s_add_i32 s52, s52, 16
	s_add_i32 s53, s53, -16
	v_mad_u64_u32 v[14:15], s[60:61], v11, s16, v[8:9]
	s_cmp_lg_u32 s53, 0
	v_mad_u64_u32 v[24:25], s[60:61], v3, s16, v[8:9]
	v_mad_u64_u32 v[28:29], s[60:61], v56, s16, v[8:9]
	v_mad_u64_u32 v[30:31], s[60:61], v16, s16, v[8:9]
	v_mad_u64_u32 v[32:33], s[60:61], v58, s16, v[8:9]
	v_mad_u64_u32 v[34:35], s[60:61], v57, s16, v[8:9]
	v_mad_u64_u32 v[36:37], s[60:61], v60, s16, v[8:9]
	v_mad_u64_u32 v[38:39], s[60:61], v59, s16, v[8:9]
	v_mad_u64_u32 v[40:41], s[60:61], v62, s16, v[8:9]
	v_mad_u64_u32 v[42:43], s[60:61], v61, s16, v[8:9]
	v_mad_u64_u32 v[44:45], s[60:61], v64, s16, v[8:9]
	v_mad_u64_u32 v[46:47], s[60:61], v63, s16, v[8:9]
	v_mad_u64_u32 v[48:49], s[60:61], v66, s16, v[8:9]
	v_mad_u64_u32 v[50:51], s[60:61], v65, s16, v[8:9]
	v_mad_u64_u32 v[52:53], s[60:61], v68, s16, v[8:9]
	v_mad_u64_u32 v[54:55], s[60:61], v67, s16, v[8:9]
	s_waitcnt vmcnt(15)
	ds_write_b32 v14, v13
	s_waitcnt vmcnt(14)
	ds_write_b32 v24, v69
	s_waitcnt vmcnt(13)
	ds_write_b32 v28, v70
	s_waitcnt vmcnt(12)
	ds_write_b32 v30, v71
	s_waitcnt vmcnt(11)
	ds_write_b32 v32, v72
	s_waitcnt vmcnt(10)
	ds_write_b32 v34, v73
	s_waitcnt vmcnt(9)
	ds_write_b32 v36, v74
	s_waitcnt vmcnt(8)
	ds_write_b32 v38, v75
	s_waitcnt vmcnt(7)
	ds_write_b32 v40, v76
	s_waitcnt vmcnt(6)
	ds_write_b32 v42, v77
	s_waitcnt vmcnt(5)
	ds_write_b32 v44, v78
	s_waitcnt vmcnt(4)
	ds_write_b32 v46, v79
	s_waitcnt vmcnt(3)
	ds_write_b32 v48, v80
	s_waitcnt vmcnt(2)
	ds_write_b32 v50, v81
	s_waitcnt vmcnt(1)
	ds_write_b32 v52, v82
	s_waitcnt vmcnt(0)
	ds_write_b32 v54, v83
	s_cbranch_scc1 .LBB0_40
	s_lshl_b32 s8, s11, 1
	s_add_u32 s8, s21, s8
	s_addc_u32 s9, s22, 0
	s_and_b32 s11, s10, 1
	s_and_b32 s12, s6, 0x7c0
	s_or_b32 s11, s12, s11
	s_and_b32 s12, 0xffff, s13
	s_lshl_b32 s12, s12, 1
	s_add_u32 s8, s8, s12
	s_waitcnt lgkmcnt(0)
	s_addc_u32 s9, s9, 0
	ds_read2_b32 v[14:15], v23 offset0:33 offset1:41
	ds_read2_b32 v[24:25], v23 offset1:8
	ds_read2_b32 v[32:33], v23 offset0:66 offset1:74
	ds_read2_b32 v[34:35], v23 offset0:99 offset1:107
	ds_read2_b32 v[36:37], v23 offset0:132 offset1:140
	ds_read2_b32 v[38:39], v23 offset0:165 offset1:173
	ds_read2_b32 v[40:41], v23 offset0:198 offset1:206
	ds_read2_b32 v[42:43], v23 offset0:231 offset1:239
	s_cmp_lt_u32 s10, 64
	v_or_b32_e32 v3, s6, v5
	v_or_b32_e32 v6, s11, v19
	s_cselect_b64 vcc, -1, 0
	v_mov_b32_e32 v13, v7
	v_cndmask_b32_e32 v3, v3, v6, vcc
	v_lshl_add_u64 v[44:45], s[8:9], 0, v[12:13]
	v_lshlrev_b32_e32 v6, 11, v3
	v_lshl_add_u64 v[46:47], v[44:45], 0, v[6:7]
	v_or_b32_e32 v3, s6, v9
	v_or_b32_e32 v6, s11, v20
	s_waitcnt lgkmcnt(6)
	v_cvt_pk_bf16_f32 v28, v24, v14
	s_waitcnt lgkmcnt(4)
	v_cvt_pk_bf16_f32 v29, v32, v34
	s_waitcnt lgkmcnt(2)
	v_cvt_pk_bf16_f32 v30, v36, v38
	s_waitcnt lgkmcnt(0)
	v_cvt_pk_bf16_f32 v31, v40, v42
	v_cndmask_b32_e32 v3, v3, v6, vcc
	global_store_dwordx4 v[46:47], v[28:31], off
	v_lshlrev_b32_e32 v6, 11, v3
	v_or_b32_e32 v3, s6, v17
	v_cvt_pk_bf16_f32 v28, v25, v15
	v_cvt_pk_bf16_f32 v29, v33, v35
	v_cvt_pk_bf16_f32 v30, v37, v39
	v_cvt_pk_bf16_f32 v31, v41, v43
	v_lshl_add_u64 v[14:15], v[44:45], 0, v[6:7]
	ds_read2_b32 v[24:25], v23 offset0:49 offset1:57
	ds_read2_b32 v[32:33], v23 offset0:16 offset1:24
	ds_read2_b32 v[34:35], v23 offset0:82 offset1:90
	ds_read2_b32 v[36:37], v23 offset0:115 offset1:123
	ds_read2_b32 v[38:39], v23 offset0:148 offset1:156
	ds_read2_b32 v[40:41], v23 offset0:181 offset1:189
	ds_read2_b32 v[42:43], v23 offset0:214 offset1:222
	ds_read2_b32 v[46:47], v23 offset0:247 offset1:255
	v_or_b32_e32 v6, s11, v21
	v_cndmask_b32_e32 v3, v3, v6, vcc
	v_lshlrev_b32_e32 v6, 11, v3
	global_store_dwordx4 v[14:15], v[28:31], off
	v_lshl_add_u64 v[14:15], v[44:45], 0, v[6:7]
	v_or_b32_e32 v3, s6, v18
	v_or_b32_e32 v6, s11, v22
	v_cndmask_b32_e32 v3, v3, v6, vcc
	s_waitcnt lgkmcnt(6)
	v_cvt_pk_bf16_f32 v28, v32, v24
	s_waitcnt lgkmcnt(4)
	v_cvt_pk_bf16_f32 v29, v34, v36
	s_waitcnt lgkmcnt(2)
	v_cvt_pk_bf16_f32 v30, v38, v40
	s_waitcnt lgkmcnt(0)
	v_cvt_pk_bf16_f32 v31, v42, v46
	v_lshlrev_b32_e32 v6, 11, v3
	global_store_dwordx4 v[14:15], v[28:31], off
	v_lshl_add_u64 v[14:15], v[44:45], 0, v[6:7]
	s_nop 0
	v_cvt_pk_bf16_f32 v28, v33, v25
	v_cvt_pk_bf16_f32 v29, v35, v37
	v_cvt_pk_bf16_f32 v30, v39, v41
	v_cvt_pk_bf16_f32 v31, v43, v47
	global_store_dwordx4 v[14:15], v[28:31], off
	s_waitcnt lgkmcnt(0)

.LBB0_45:
	s_lshl_b32 s51, s11, 1
	s_lshl_b32 s52, s12, 1
	v_or_b32_e32 v6, s52, v16
	s_add_i32 s60, s51, 4
	s_add_i32 s61, s52, 4
	v_mov_b32_e32 v29, v7
	s_add_i32 s63, s52, 8
	v_lshlrev_b64 v[42:43], 11, v[6:7]
	v_or_b32_e32 v28, s60, v3
	v_or_b32_e32 v6, s61, v16
	v_mov_b32_e32 v25, v7
	v_or_b32_e32 v24, s51, v3
	s_add_i32 s65, s52, 12
	v_lshlrev_b64 v[28:29], 11, v[28:29]
	v_lshlrev_b64 v[44:45], 11, v[6:7]
	v_or_b32_e32 v6, s63, v16
	s_add_i32 s62, s51, 8
	s_add_i32 s64, s51, 12
	s_add_i32 s67, s52, 16
	v_lshlrev_b64 v[24:25], 11, v[24:25]
	v_lshl_add_u64 v[42:43], v[14:15], 0, v[42:43]
	v_lshl_add_u64 v[28:29], v[14:15], 0, v[28:29]
	v_lshlrev_b64 v[46:47], 11, v[6:7]
	v_or_b32_e32 v6, s65, v16
	v_mov_b32_e32 v31, v7
	v_mov_b32_e32 v33, v7
	s_add_i32 s69, s52, 20
	v_or_b32_e32 v30, s62, v3
	v_or_b32_e32 v32, s64, v3
	v_lshl_add_u64 v[24:25], v[14:15], 0, v[24:25]
	v_lshl_add_u64 v[44:45], v[14:15], 0, v[44:45]
	global_load_dword v11, v[42:43], off nt
	global_load_dword v13, v[24:25], off nt
	global_load_dword v58, v[44:45], off nt
	global_load_dword v59, v[28:29], off nt
	v_lshlrev_b64 v[28:29], 11, v[6:7]
	v_or_b32_e32 v6, s67, v16
	s_add_i32 s66, s51, 16
	s_add_i32 s68, s51, 20
	s_add_i32 s71, s52, 24
	v_lshlrev_b64 v[30:31], 11, v[30:31]
	v_lshlrev_b64 v[32:33], 11, v[32:33]
	v_lshl_add_u64 v[24:25], v[14:15], 0, v[46:47]
	v_lshl_add_u64 v[28:29], v[14:15], 0, v[28:29]
	v_lshlrev_b64 v[42:43], 11, v[6:7]
	v_or_b32_e32 v6, s69, v16
	v_mov_b32_e32 v35, v7
	v_mov_b32_e32 v37, v7
	s_add_i32 s70, s51, 24
	s_add_i32 s72, s51, 28
	s_add_i32 s73, s52, 28
	v_or_b32_e32 v34, s66, v3
	v_or_b32_e32 v36, s68, v3
	v_lshl_add_u64 v[30:31], v[14:15], 0, v[30:31]
	v_lshl_add_u64 v[32:33], v[14:15], 0, v[32:33]
	global_load_dword v60, v[24:25], off nt
	global_load_dword v61, v[30:31], off nt
	global_load_dword v62, v[28:29], off nt
	global_load_dword v63, v[32:33], off nt
	v_lshlrev_b64 v[28:29], 11, v[6:7]
	v_or_b32_e32 v6, s71, v16
	v_mov_b32_e32 v39, v7
	v_mov_b32_e32 v41, v7
	v_or_b32_e32 v38, s70, v3
	v_or_b32_e32 v40, s72, v3
	v_lshlrev_b64 v[34:35], 11, v[34:35]
	v_lshlrev_b64 v[36:37], 11, v[36:37]
	v_lshl_add_u64 v[24:25], v[14:15], 0, v[42:43]
	v_lshl_add_u64 v[28:29], v[14:15], 0, v[28:29]
	v_lshlrev_b64 v[30:31], 11, v[6:7]
	v_or_b32_e32 v6, s73, v16
	v_lshlrev_b64 v[38:39], 11, v[38:39]
	v_lshlrev_b64 v[40:41], 11, v[40:41]
	v_lshl_add_u64 v[34:35], v[14:15], 0, v[34:35]
	v_lshl_add_u64 v[36:37], v[14:15], 0, v[36:37]
	global_load_dword v64, v[24:25], off nt
	global_load_dword v65, v[34:35], off nt
	global_load_dword v66, v[28:29], off nt
	global_load_dword v67, v[36:37], off nt
	v_lshl_add_u64 v[24:25], v[14:15], 0, v[30:31]
	v_lshlrev_b64 v[28:29], 11, v[6:7]
	v_lshl_add_u64 v[38:39], v[14:15], 0, v[38:39]
	v_lshl_add_u64 v[40:41], v[14:15], 0, v[40:41]
	v_lshl_add_u64 v[28:29], v[14:15], 0, v[28:29]
	global_load_dword v6, v[24:25], off nt
	global_load_dword v68, v[38:39], off nt
	global_load_dword v69, v[28:29], off nt
	global_load_dword v70, v[40:41], off nt
	v_or_b32_e32 v28, s51, v1
	v_or_b32_e32 v24, s52, v2
	s_add_i32 s12, s12, 16
	s_add_i32 s11, s11, 16
	s_add_i32 s13, s13, -16
	v_mad_u64_u32 v[24:25], s[52:53], v24, s16, v[8:9]
	v_mad_u64_u32 v[28:29], s[52:53], v28, s16, v[8:9]
	v_or_b32_e32 v25, s60, v1
	v_or_b32_e32 v29, s61, v2
	v_or_b32_e32 v36, s62, v1
	v_or_b32_e32 v34, s63, v2
	v_or_b32_e32 v40, s64, v1
	v_or_b32_e32 v38, s65, v2
	v_or_b32_e32 v44, s66, v1
	v_or_b32_e32 v42, s67, v2
	v_or_b32_e32 v48, s68, v1
	v_or_b32_e32 v46, s69, v2
	v_or_b32_e32 v52, s70, v1
	v_or_b32_e32 v50, s71, v2
	v_or_b32_e32 v56, s72, v1
	v_or_b32_e32 v54, s73, v2
	s_cmp_lg_u32 s13, 0
	v_mad_u64_u32 v[30:31], s[52:53], v29, s16, v[8:9]
	v_mad_u64_u32 v[32:33], s[52:53], v25, s16, v[8:9]
	v_mad_u64_u32 v[34:35], s[52:53], v34, s16, v[8:9]
	v_mad_u64_u32 v[36:37], s[52:53], v36, s16, v[8:9]
	v_mad_u64_u32 v[38:39], s[52:53], v38, s16, v[8:9]
	v_mad_u64_u32 v[40:41], s[52:53], v40, s16, v[8:9]
	v_mad_u64_u32 v[42:43], s[52:53], v42, s16, v[8:9]
	v_mad_u64_u32 v[44:45], s[52:53], v44, s16, v[8:9]
	v_mad_u64_u32 v[46:47], s[52:53], v46, s16, v[8:9]
	v_mad_u64_u32 v[48:49], s[52:53], v48, s16, v[8:9]
	v_mad_u64_u32 v[50:51], s[52:53], v50, s16, v[8:9]
	v_mad_u64_u32 v[52:53], s[52:53], v52, s16, v[8:9]
	v_mad_u64_u32 v[54:55], s[52:53], v54, s16, v[8:9]
	v_mad_u64_u32 v[56:57], s[52:53], v56, s16, v[8:9]
	s_waitcnt vmcnt(15)
	ds_write_b32 v24, v11
	s_waitcnt vmcnt(14)
	ds_write_b32 v28, v13
	s_waitcnt vmcnt(13)
	ds_write_b32 v30, v58
	s_waitcnt vmcnt(12)
	ds_write_b32 v32, v59
	s_waitcnt vmcnt(11)
	ds_write_b32 v34, v60
	s_waitcnt vmcnt(10)
	ds_write_b32 v36, v61
	s_waitcnt vmcnt(9)
	ds_write_b32 v38, v62
	s_waitcnt vmcnt(8)
	ds_write_b32 v40, v63
	s_waitcnt vmcnt(7)
	ds_write_b32 v42, v64
	s_waitcnt vmcnt(6)
	ds_write_b32 v44, v65
	s_waitcnt vmcnt(5)
	ds_write_b32 v46, v66
	s_waitcnt vmcnt(4)
	ds_write_b32 v48, v67
	s_waitcnt vmcnt(3)
	ds_write_b32 v50, v6
	s_waitcnt vmcnt(2)
	ds_write_b32 v52, v68
	s_waitcnt vmcnt(1)
	ds_write_b32 v54, v69
	s_waitcnt vmcnt(0)
	ds_write_b32 v56, v70
	s_cbranch_scc1 .LBB0_45
	s_lshl_b64 s[8:9], s[8:9], 1
	s_waitcnt lgkmcnt(0)
	s_add_u32 s8, s23, s8
	ds_read2_b32 v[14:15], v23 offset0:33 offset1:41
	ds_read2_b32 v[24:25], v23 offset1:8
	ds_read2_b32 v[32:33], v23 offset0:66 offset1:74
	ds_read2_b32 v[34:35], v23 offset0:99 offset1:107
	ds_read2_b32 v[36:37], v23 offset0:132 offset1:140
	ds_read2_b32 v[38:39], v23 offset0:165 offset1:173
	ds_read2_b32 v[40:41], v23 offset0:198 offset1:206
	ds_read2_b32 v[42:43], v23 offset0:231 offset1:239
	s_addc_u32 s9, s34, s9
	s_lshl_b32 s10, s10, 1
	s_add_u32 s8, s8, s10
	s_addc_u32 s9, s9, 0
	v_mov_b32_e32 v13, v7
	v_or_b32_e32 v3, s6, v5
	v_lshl_add_u64 v[44:45], s[8:9], 0, v[12:13]
	v_lshlrev_b32_e32 v6, 10, v3
	s_waitcnt lgkmcnt(6)
	v_cvt_pk_bf16_f32 v28, v24, v14
	s_waitcnt lgkmcnt(4)
	v_cvt_pk_bf16_f32 v29, v32, v34
	s_waitcnt lgkmcnt(2)
	v_cvt_pk_bf16_f32 v30, v36, v38
	s_waitcnt lgkmcnt(0)
	v_cvt_pk_bf16_f32 v31, v40, v42
	v_lshl_add_u64 v[46:47], v[44:45], 0, v[6:7]
	global_store_dwordx4 v[46:47], v[28:31], off
	v_or_b32_e32 v3, s6, v9
	v_lshlrev_b32_e32 v6, 10, v3
	v_cvt_pk_bf16_f32 v28, v25, v15
	v_cvt_pk_bf16_f32 v29, v33, v35
	v_cvt_pk_bf16_f32 v30, v37, v39
	v_cvt_pk_bf16_f32 v31, v41, v43
	ds_read2_b32 v[24:25], v23 offset0:49 offset1:57
	ds_read2_b32 v[32:33], v23 offset0:16 offset1:24
	ds_read2_b32 v[34:35], v23 offset0:82 offset1:90
	ds_read2_b32 v[36:37], v23 offset0:115 offset1:123
	ds_read2_b32 v[38:39], v23 offset0:148 offset1:156
	ds_read2_b32 v[40:41], v23 offset0:181 offset1:189
	ds_read2_b32 v[42:43], v23 offset0:214 offset1:222
	ds_read2_b32 v[46:47], v23 offset0:247 offset1:255
	v_or_b32_e32 v3, s6, v17
	v_lshl_add_u64 v[14:15], v[44:45], 0, v[6:7]
	v_lshlrev_b32_e32 v6, 10, v3
	v_or_b32_e32 v3, s6, v18
	global_store_dwordx4 v[14:15], v[28:31], off
	v_lshl_add_u64 v[14:15], v[44:45], 0, v[6:7]
	v_lshlrev_b32_e32 v6, 10, v3
	s_waitcnt lgkmcnt(6)
	v_cvt_pk_bf16_f32 v28, v32, v24
	s_waitcnt lgkmcnt(4)
	v_cvt_pk_bf16_f32 v29, v34, v36
	s_waitcnt lgkmcnt(2)
	v_cvt_pk_bf16_f32 v30, v38, v40
	s_waitcnt lgkmcnt(0)
	v_cvt_pk_bf16_f32 v31, v42, v46
	global_store_dwordx4 v[14:15], v[28:31], off
	v_lshl_add_u64 v[14:15], v[44:45], 0, v[6:7]
	s_nop 0
	v_cvt_pk_bf16_f32 v28, v33, v25
	v_cvt_pk_bf16_f32 v29, v35, v37
	v_cvt_pk_bf16_f32 v30, v39, v41
	v_cvt_pk_bf16_f32 v31, v43, v47
	global_store_dwordx4 v[14:15], v[28:31], off
	s_waitcnt lgkmcnt(0)

.LBB0_50:
	s_lshl_b32 s51, s11, 1
	s_lshl_b32 s52, s12, 1
	v_or_b32_e32 v6, s52, v16
	s_add_i32 s60, s51, 4
	s_add_i32 s61, s52, 4
	v_mov_b32_e32 v29, v7
	s_add_i32 s63, s52, 8
	v_lshlrev_b64 v[42:43], 12, v[6:7]
	v_or_b32_e32 v28, s60, v3
	v_or_b32_e32 v6, s61, v16
	v_mov_b32_e32 v25, v7
	v_or_b32_e32 v24, s51, v3
	s_add_i32 s65, s52, 12
	v_lshlrev_b64 v[28:29], 12, v[28:29]
	v_lshlrev_b64 v[44:45], 12, v[6:7]
	v_or_b32_e32 v6, s63, v16
	s_add_i32 s62, s51, 8
	s_add_i32 s64, s51, 12
	s_add_i32 s67, s52, 16
	v_lshlrev_b64 v[24:25], 12, v[24:25]
	v_lshl_add_u64 v[42:43], v[14:15], 0, v[42:43]
	v_lshl_add_u64 v[28:29], v[14:15], 0, v[28:29]
	v_lshlrev_b64 v[46:47], 12, v[6:7]
	v_or_b32_e32 v6, s65, v16
	v_mov_b32_e32 v31, v7
	v_mov_b32_e32 v33, v7
	s_add_i32 s69, s52, 20
	v_or_b32_e32 v30, s62, v3
	v_or_b32_e32 v32, s64, v3
	v_lshl_add_u64 v[24:25], v[14:15], 0, v[24:25]
	v_lshl_add_u64 v[44:45], v[14:15], 0, v[44:45]
	global_load_dword v11, v[42:43], off nt
	global_load_dword v13, v[24:25], off nt
	global_load_dword v58, v[44:45], off nt
	global_load_dword v59, v[28:29], off nt
	v_lshlrev_b64 v[28:29], 12, v[6:7]
	v_or_b32_e32 v6, s67, v16
	s_add_i32 s66, s51, 16
	s_add_i32 s68, s51, 20
	s_add_i32 s71, s52, 24
	v_lshlrev_b64 v[30:31], 12, v[30:31]
	v_lshlrev_b64 v[32:33], 12, v[32:33]
	v_lshl_add_u64 v[24:25], v[14:15], 0, v[46:47]
	v_lshl_add_u64 v[28:29], v[14:15], 0, v[28:29]
	v_lshlrev_b64 v[42:43], 12, v[6:7]
	v_or_b32_e32 v6, s69, v16
	v_mov_b32_e32 v35, v7
	v_mov_b32_e32 v37, v7
	s_add_i32 s70, s51, 24
	s_add_i32 s72, s51, 28
	s_add_i32 s73, s52, 28
	v_or_b32_e32 v34, s66, v3
	v_or_b32_e32 v36, s68, v3
	v_lshl_add_u64 v[30:31], v[14:15], 0, v[30:31]
	v_lshl_add_u64 v[32:33], v[14:15], 0, v[32:33]
	global_load_dword v60, v[24:25], off nt
	global_load_dword v61, v[30:31], off nt
	global_load_dword v62, v[28:29], off nt
	global_load_dword v63, v[32:33], off nt
	v_lshlrev_b64 v[28:29], 12, v[6:7]
	v_or_b32_e32 v6, s71, v16
	v_mov_b32_e32 v39, v7
	v_mov_b32_e32 v41, v7
	v_or_b32_e32 v38, s70, v3
	v_or_b32_e32 v40, s72, v3
	v_lshlrev_b64 v[34:35], 12, v[34:35]
	v_lshlrev_b64 v[36:37], 12, v[36:37]
	v_lshl_add_u64 v[24:25], v[14:15], 0, v[42:43]
	v_lshl_add_u64 v[28:29], v[14:15], 0, v[28:29]
	v_lshlrev_b64 v[30:31], 12, v[6:7]
	v_or_b32_e32 v6, s73, v16
	v_lshlrev_b64 v[38:39], 12, v[38:39]
	v_lshlrev_b64 v[40:41], 12, v[40:41]
	v_lshl_add_u64 v[34:35], v[14:15], 0, v[34:35]
	v_lshl_add_u64 v[36:37], v[14:15], 0, v[36:37]
	global_load_dword v64, v[24:25], off nt
	global_load_dword v65, v[34:35], off nt
	global_load_dword v66, v[28:29], off nt
	global_load_dword v67, v[36:37], off nt
	v_lshl_add_u64 v[24:25], v[14:15], 0, v[30:31]
	v_lshlrev_b64 v[28:29], 12, v[6:7]
	v_lshl_add_u64 v[38:39], v[14:15], 0, v[38:39]
	v_lshl_add_u64 v[40:41], v[14:15], 0, v[40:41]
	v_lshl_add_u64 v[28:29], v[14:15], 0, v[28:29]
	global_load_dword v6, v[24:25], off nt
	global_load_dword v68, v[38:39], off nt
	global_load_dword v69, v[28:29], off nt
	global_load_dword v70, v[40:41], off nt
	v_or_b32_e32 v28, s51, v1
	v_or_b32_e32 v24, s52, v2
	s_add_i32 s12, s12, 16
	s_add_i32 s11, s11, 16
	s_add_i32 s13, s13, -16
	v_mad_u64_u32 v[24:25], s[52:53], v24, s16, v[8:9]
	v_mad_u64_u32 v[28:29], s[52:53], v28, s16, v[8:9]
	v_or_b32_e32 v25, s60, v1
	v_or_b32_e32 v29, s61, v2
	v_or_b32_e32 v36, s62, v1
	v_or_b32_e32 v34, s63, v2
	v_or_b32_e32 v40, s64, v1
	v_or_b32_e32 v38, s65, v2
	v_or_b32_e32 v44, s66, v1
	v_or_b32_e32 v42, s67, v2
	v_or_b32_e32 v48, s68, v1
	v_or_b32_e32 v46, s69, v2
	v_or_b32_e32 v52, s70, v1
	v_or_b32_e32 v50, s71, v2
	v_or_b32_e32 v56, s72, v1
	v_or_b32_e32 v54, s73, v2
	s_cmp_lg_u32 s13, 0
	v_mad_u64_u32 v[30:31], s[52:53], v29, s16, v[8:9]
	v_mad_u64_u32 v[32:33], s[52:53], v25, s16, v[8:9]
	v_mad_u64_u32 v[34:35], s[52:53], v34, s16, v[8:9]
	v_mad_u64_u32 v[36:37], s[52:53], v36, s16, v[8:9]
	v_mad_u64_u32 v[38:39], s[52:53], v38, s16, v[8:9]
	v_mad_u64_u32 v[40:41], s[52:53], v40, s16, v[8:9]
	v_mad_u64_u32 v[42:43], s[52:53], v42, s16, v[8:9]
	v_mad_u64_u32 v[44:45], s[52:53], v44, s16, v[8:9]
	v_mad_u64_u32 v[46:47], s[52:53], v46, s16, v[8:9]
	v_mad_u64_u32 v[48:49], s[52:53], v48, s16, v[8:9]
	v_mad_u64_u32 v[50:51], s[52:53], v50, s16, v[8:9]
	v_mad_u64_u32 v[52:53], s[52:53], v52, s16, v[8:9]
	v_mad_u64_u32 v[54:55], s[52:53], v54, s16, v[8:9]
	v_mad_u64_u32 v[56:57], s[52:53], v56, s16, v[8:9]
	s_waitcnt vmcnt(15)
	ds_write_b32 v24, v11
	s_waitcnt vmcnt(14)
	ds_write_b32 v28, v13
	s_waitcnt vmcnt(13)
	ds_write_b32 v30, v58
	s_waitcnt vmcnt(12)
	ds_write_b32 v32, v59
	s_waitcnt vmcnt(11)
	ds_write_b32 v34, v60
	s_waitcnt vmcnt(10)
	ds_write_b32 v36, v61
	s_waitcnt vmcnt(9)
	ds_write_b32 v38, v62
	s_waitcnt vmcnt(8)
	ds_write_b32 v40, v63
	s_waitcnt vmcnt(7)
	ds_write_b32 v42, v64
	s_waitcnt vmcnt(6)
	ds_write_b32 v44, v65
	s_waitcnt vmcnt(5)
	ds_write_b32 v46, v66
	s_waitcnt vmcnt(4)
	ds_write_b32 v48, v67
	s_waitcnt vmcnt(3)
	ds_write_b32 v50, v6
	s_waitcnt vmcnt(2)
	ds_write_b32 v52, v68
	s_waitcnt vmcnt(1)
	ds_write_b32 v54, v69
	s_waitcnt vmcnt(0)
	ds_write_b32 v56, v70
	s_cbranch_scc1 .LBB0_50
	s_lshl_b64 s[8:9], s[8:9], 1
	s_waitcnt lgkmcnt(0)
	s_add_u32 s8, s35, s8
	ds_read2_b32 v[14:15], v23 offset0:33 offset1:41
	ds_read2_b32 v[24:25], v23 offset1:8
	ds_read2_b32 v[32:33], v23 offset0:66 offset1:74
	ds_read2_b32 v[34:35], v23 offset0:99 offset1:107
	ds_read2_b32 v[36:37], v23 offset0:132 offset1:140
	ds_read2_b32 v[38:39], v23 offset0:165 offset1:173
	ds_read2_b32 v[40:41], v23 offset0:198 offset1:206
	ds_read2_b32 v[42:43], v23 offset0:231 offset1:239
	s_addc_u32 s9, s44, s9
	s_lshl_b32 s10, s10, 1
	s_add_u32 s8, s8, s10
	s_addc_u32 s9, s9, 0
	v_mov_b32_e32 v13, v7
	v_or_b32_e32 v3, s6, v5
	v_lshl_add_u64 v[44:45], s[8:9], 0, v[12:13]
	v_lshlrev_b32_e32 v6, 11, v3
	s_waitcnt lgkmcnt(6)
	v_cvt_pk_bf16_f32 v28, v24, v14
	s_waitcnt lgkmcnt(4)
	v_cvt_pk_bf16_f32 v29, v32, v34
	s_waitcnt lgkmcnt(2)
	v_cvt_pk_bf16_f32 v30, v36, v38
	s_waitcnt lgkmcnt(0)
	v_cvt_pk_bf16_f32 v31, v40, v42
	v_lshl_add_u64 v[46:47], v[44:45], 0, v[6:7]
	global_store_dwordx4 v[46:47], v[28:31], off
	v_or_b32_e32 v3, s6, v9
	v_lshlrev_b32_e32 v6, 11, v3
	v_cvt_pk_bf16_f32 v28, v25, v15
	v_cvt_pk_bf16_f32 v29, v33, v35
	v_cvt_pk_bf16_f32 v30, v37, v39
	v_cvt_pk_bf16_f32 v31, v41, v43
	ds_read2_b32 v[24:25], v23 offset0:49 offset1:57
	ds_read2_b32 v[32:33], v23 offset0:16 offset1:24
	ds_read2_b32 v[34:35], v23 offset0:82 offset1:90
	ds_read2_b32 v[36:37], v23 offset0:115 offset1:123
	ds_read2_b32 v[38:39], v23 offset0:148 offset1:156
	ds_read2_b32 v[40:41], v23 offset0:181 offset1:189
	ds_read2_b32 v[42:43], v23 offset0:214 offset1:222
	ds_read2_b32 v[46:47], v23 offset0:247 offset1:255
	v_or_b32_e32 v3, s6, v17
	v_lshl_add_u64 v[14:15], v[44:45], 0, v[6:7]
	v_lshlrev_b32_e32 v6, 11, v3
	v_or_b32_e32 v3, s6, v18
	global_store_dwordx4 v[14:15], v[28:31], off
	v_lshl_add_u64 v[14:15], v[44:45], 0, v[6:7]
	v_lshlrev_b32_e32 v6, 11, v3
	s_waitcnt lgkmcnt(6)
	v_cvt_pk_bf16_f32 v28, v32, v24
	s_waitcnt lgkmcnt(4)
	v_cvt_pk_bf16_f32 v29, v34, v36
	s_waitcnt lgkmcnt(2)
	v_cvt_pk_bf16_f32 v30, v38, v40
	s_waitcnt lgkmcnt(0)
	v_cvt_pk_bf16_f32 v31, v42, v46
	global_store_dwordx4 v[14:15], v[28:31], off
	v_lshl_add_u64 v[14:15], v[44:45], 0, v[6:7]
	s_nop 0
	v_cvt_pk_bf16_f32 v28, v33, v25
	v_cvt_pk_bf16_f32 v29, v35, v37
	v_cvt_pk_bf16_f32 v30, v39, v41
	v_cvt_pk_bf16_f32 v31, v43, v47
	global_store_dwordx4 v[14:15], v[28:31], off
	s_waitcnt lgkmcnt(0)

.LBB0_55:
	s_lshl_b32 s51, s6, 1
	s_lshl_b32 s52, s9, 1
	v_or_b32_e32 v28, s52, v6
	s_add_i32 s53, s51, 4
	s_add_i32 s60, s52, 4
	s_add_i32 s61, s51, 8
	s_add_i32 s62, s52, 8
	s_add_i32 s63, s51, 12
	s_add_i32 s66, s52, 12
	s_add_i32 s67, s51, 16
	s_add_i32 s68, s52, 16
	s_add_i32 s69, s51, 20
	s_add_i32 s70, s52, 20
	s_add_i32 s71, s51, 24
	s_add_i32 s72, s52, 24
	s_add_i32 s73, s51, 28
	s_add_i32 s74, s52, 28
	v_or_b32_e32 v24, s51, v3
	v_ashrrev_i32_e32 v29, 31, v28
	v_or_b32_e32 v30, s53, v3
	v_or_b32_e32 v32, s60, v6
	v_or_b32_e32 v34, s61, v3
	v_or_b32_e32 v36, s62, v6
	v_or_b32_e32 v38, s63, v3
	v_or_b32_e32 v40, s66, v6
	v_or_b32_e32 v42, s67, v3
	v_or_b32_e32 v44, s68, v6
	v_or_b32_e32 v46, s69, v3
	v_or_b32_e32 v48, s70, v6
	v_or_b32_e32 v50, s71, v3
	v_or_b32_e32 v52, s72, v6
	v_or_b32_e32 v54, s73, v3
	v_or_b32_e32 v56, s74, v6
	v_ashrrev_i32_e32 v25, 31, v24
	v_lshlrev_b64 v[28:29], 13, v[28:29]
	v_ashrrev_i32_e32 v33, 31, v32
	v_ashrrev_i32_e32 v31, 31, v30
	v_ashrrev_i32_e32 v37, 31, v36
	v_ashrrev_i32_e32 v35, 31, v34
	v_ashrrev_i32_e32 v41, 31, v40
	v_ashrrev_i32_e32 v39, 31, v38
	v_ashrrev_i32_e32 v45, 31, v44
	v_ashrrev_i32_e32 v43, 31, v42
	v_ashrrev_i32_e32 v49, 31, v48
	v_ashrrev_i32_e32 v47, 31, v46
	v_ashrrev_i32_e32 v53, 31, v52
	v_ashrrev_i32_e32 v51, 31, v50
	v_ashrrev_i32_e32 v57, 31, v56
	v_ashrrev_i32_e32 v55, 31, v54
	v_lshlrev_b64 v[24:25], 13, v[24:25]
	v_lshl_add_u64 v[28:29], v[14:15], 0, v[28:29]
	v_lshlrev_b64 v[30:31], 13, v[30:31]
	v_lshlrev_b64 v[32:33], 13, v[32:33]
	v_lshlrev_b64 v[34:35], 13, v[34:35]
	v_lshlrev_b64 v[36:37], 13, v[36:37]
	v_lshlrev_b64 v[38:39], 13, v[38:39]
	v_lshlrev_b64 v[40:41], 13, v[40:41]
	v_lshlrev_b64 v[42:43], 13, v[42:43]
	v_lshlrev_b64 v[44:45], 13, v[44:45]
	v_lshlrev_b64 v[46:47], 13, v[46:47]
	v_lshlrev_b64 v[48:49], 13, v[48:49]
	v_lshlrev_b64 v[50:51], 13, v[50:51]
	v_lshlrev_b64 v[52:53], 13, v[52:53]
	v_lshlrev_b64 v[54:55], 13, v[54:55]
	v_lshlrev_b64 v[56:57], 13, v[56:57]
	v_lshl_add_u64 v[24:25], v[14:15], 0, v[24:25]
	v_lshl_add_u64 v[32:33], v[14:15], 0, v[32:33]
	v_lshl_add_u64 v[30:31], v[14:15], 0, v[30:31]
	v_lshl_add_u64 v[36:37], v[14:15], 0, v[36:37]
	v_lshl_add_u64 v[34:35], v[14:15], 0, v[34:35]
	v_lshl_add_u64 v[40:41], v[14:15], 0, v[40:41]
	v_lshl_add_u64 v[38:39], v[14:15], 0, v[38:39]
	v_lshl_add_u64 v[44:45], v[14:15], 0, v[44:45]
	v_lshl_add_u64 v[42:43], v[14:15], 0, v[42:43]
	v_lshl_add_u64 v[48:49], v[14:15], 0, v[48:49]
	v_lshl_add_u64 v[46:47], v[14:15], 0, v[46:47]
	v_lshl_add_u64 v[52:53], v[14:15], 0, v[52:53]
	v_lshl_add_u64 v[50:51], v[14:15], 0, v[50:51]
	v_lshl_add_u64 v[56:57], v[14:15], 0, v[56:57]
	v_lshl_add_u64 v[54:55], v[14:15], 0, v[54:55]
	global_load_dword v11, v[28:29], off nt
	global_load_dword v13, v[24:25], off nt
	global_load_dword v16, v[32:33], off nt
	global_load_dword v58, v[30:31], off nt
	global_load_dword v59, v[36:37], off nt
	global_load_dword v60, v[34:35], off nt
	global_load_dword v61, v[40:41], off nt
	global_load_dword v62, v[38:39], off nt
	global_load_dword v63, v[44:45], off nt
	global_load_dword v64, v[42:43], off nt
	global_load_dword v65, v[48:49], off nt
	global_load_dword v66, v[46:47], off nt
	global_load_dword v67, v[52:53], off nt
	global_load_dword v68, v[50:51], off nt
	global_load_dword v69, v[56:57], off nt
	global_load_dword v70, v[54:55], off nt
	v_or_b32_e32 v28, s51, v1
	v_or_b32_e32 v24, s52, v2
	s_add_i32 s9, s9, 16
	s_add_i32 s6, s6, 16
	s_add_i32 s13, s13, -16
	v_mad_u64_u32 v[24:25], s[64:65], v24, s16, v[8:9]
	v_mad_u64_u32 v[28:29], s[64:65], v28, s16, v[8:9]
	v_or_b32_e32 v25, s53, v1
	v_or_b32_e32 v29, s60, v2
	v_or_b32_e32 v36, s61, v1
	v_or_b32_e32 v34, s62, v2
	v_or_b32_e32 v40, s63, v1
	v_or_b32_e32 v38, s66, v2
	v_or_b32_e32 v44, s67, v1
	v_or_b32_e32 v42, s68, v2
	v_or_b32_e32 v48, s69, v1
	v_or_b32_e32 v46, s70, v2
	v_or_b32_e32 v52, s71, v1
	v_or_b32_e32 v50, s72, v2
	v_or_b32_e32 v56, s73, v1
	v_or_b32_e32 v54, s74, v2
	s_cmp_lg_u32 s13, 0
	v_mad_u64_u32 v[30:31], s[52:53], v29, s16, v[8:9]
	v_mad_u64_u32 v[32:33], s[52:53], v25, s16, v[8:9]
	v_mad_u64_u32 v[34:35], s[52:53], v34, s16, v[8:9]
	v_mad_u64_u32 v[36:37], s[52:53], v36, s16, v[8:9]
	v_mad_u64_u32 v[38:39], s[52:53], v38, s16, v[8:9]
	v_mad_u64_u32 v[40:41], s[52:53], v40, s16, v[8:9]
	v_mad_u64_u32 v[42:43], s[52:53], v42, s16, v[8:9]
	v_mad_u64_u32 v[44:45], s[52:53], v44, s16, v[8:9]
	v_mad_u64_u32 v[46:47], s[52:53], v46, s16, v[8:9]
	v_mad_u64_u32 v[48:49], s[52:53], v48, s16, v[8:9]
	v_mad_u64_u32 v[50:51], s[52:53], v50, s16, v[8:9]
	v_mad_u64_u32 v[52:53], s[52:53], v52, s16, v[8:9]
	v_mad_u64_u32 v[54:55], s[52:53], v54, s16, v[8:9]
	v_mad_u64_u32 v[56:57], s[52:53], v56, s16, v[8:9]
	s_waitcnt vmcnt(15)
	ds_write_b32 v24, v11
	s_waitcnt vmcnt(14)
	ds_write_b32 v28, v13
	s_waitcnt vmcnt(13)
	ds_write_b32 v30, v16
	s_waitcnt vmcnt(12)
	ds_write_b32 v32, v58
	s_waitcnt vmcnt(11)
	ds_write_b32 v34, v59
	s_waitcnt vmcnt(10)
	ds_write_b32 v36, v60
	s_waitcnt vmcnt(9)
	ds_write_b32 v38, v61
	s_waitcnt vmcnt(8)
	ds_write_b32 v40, v62
	s_waitcnt vmcnt(7)
	ds_write_b32 v42, v63
	s_waitcnt vmcnt(6)
	ds_write_b32 v44, v64
	s_waitcnt vmcnt(5)
	ds_write_b32 v46, v65
	s_waitcnt vmcnt(4)
	ds_write_b32 v48, v66
	s_waitcnt vmcnt(3)
	ds_write_b32 v50, v67
	s_waitcnt vmcnt(2)
	ds_write_b32 v52, v68
	s_waitcnt vmcnt(1)
	ds_write_b32 v54, v69
	s_waitcnt vmcnt(0)
	ds_write_b32 v56, v70
	s_cbranch_scc1 .LBB0_55
	s_lshl_b64 s[10:11], s[10:11], 1
	s_add_u32 s6, s45, s10
	s_waitcnt lgkmcnt(0)
	s_addc_u32 s9, s46, s11
	s_ashr_i32 s13, s12, 31
	ds_read2_b32 v[14:15], v23 offset0:33 offset1:41
	ds_read2_b32 v[24:25], v23 offset1:8
	ds_read2_b32 v[32:33], v23 offset0:66 offset1:74
	ds_read2_b32 v[34:35], v23 offset0:99 offset1:107
	ds_read2_b32 v[36:37], v23 offset0:132 offset1:140
	ds_read2_b32 v[38:39], v23 offset0:165 offset1:173
	ds_read2_b32 v[40:41], v23 offset0:198 offset1:206
	ds_read2_b32 v[42:43], v23 offset0:231 offset1:239
	s_lshl_b64 s[10:11], s[12:13], 1
	s_add_u32 s10, s6, s10
	v_or_b32_e32 v46, s8, v5
	s_addc_u32 s11, s9, s11
	v_mov_b32_e32 v13, v7
	v_ashrrev_i32_e32 v47, 31, v46
	v_lshl_add_u64 v[44:45], s[10:11], 0, v[12:13]
	v_lshlrev_b64 v[46:47], 11, v[46:47]
	s_waitcnt lgkmcnt(6)
	v_cvt_pk_bf16_f32 v28, v24, v14
	s_waitcnt lgkmcnt(4)
	v_cvt_pk_bf16_f32 v29, v32, v34
	s_waitcnt lgkmcnt(2)
	v_cvt_pk_bf16_f32 v30, v36, v38
	s_waitcnt lgkmcnt(0)
	v_cvt_pk_bf16_f32 v31, v40, v42
	v_lshl_add_u64 v[46:47], v[44:45], 0, v[46:47]
	v_or_b32_e32 v14, s8, v9
	global_store_dwordx4 v[46:47], v[28:31], off
	s_nop 1
	v_cvt_pk_bf16_f32 v28, v25, v15
	v_ashrrev_i32_e32 v15, 31, v14
	v_cvt_pk_bf16_f32 v29, v33, v35
	v_cvt_pk_bf16_f32 v30, v37, v39
	v_cvt_pk_bf16_f32 v31, v41, v43
	v_lshlrev_b64 v[14:15], 11, v[14:15]
	ds_read2_b32 v[24:25], v23 offset0:49 offset1:57
	ds_read2_b32 v[32:33], v23 offset0:16 offset1:24
	ds_read2_b32 v[34:35], v23 offset0:82 offset1:90
	ds_read2_b32 v[36:37], v23 offset0:115 offset1:123
	ds_read2_b32 v[38:39], v23 offset0:148 offset1:156
	ds_read2_b32 v[40:41], v23 offset0:181 offset1:189
	ds_read2_b32 v[42:43], v23 offset0:214 offset1:222
	ds_read2_b32 v[46:47], v23 offset0:247 offset1:255
	v_lshl_add_u64 v[14:15], v[44:45], 0, v[14:15]
	global_store_dwordx4 v[14:15], v[28:31], off
	v_or_b32_e32 v14, s8, v17
	v_ashrrev_i32_e32 v15, 31, v14
	v_lshlrev_b64 v[14:15], 11, v[14:15]
	s_waitcnt lgkmcnt(6)
	v_cvt_pk_bf16_f32 v28, v32, v24
	s_waitcnt lgkmcnt(4)
	v_cvt_pk_bf16_f32 v29, v34, v36
	s_waitcnt lgkmcnt(2)
	v_cvt_pk_bf16_f32 v30, v38, v40
	s_waitcnt lgkmcnt(0)
	v_cvt_pk_bf16_f32 v31, v42, v46
	v_lshl_add_u64 v[14:15], v[44:45], 0, v[14:15]
	global_store_dwordx4 v[14:15], v[28:31], off
	v_or_b32_e32 v14, s8, v18
	v_ashrrev_i32_e32 v15, 31, v14
	v_lshlrev_b64 v[14:15], 11, v[14:15]
	v_cvt_pk_bf16_f32 v28, v33, v25
	v_cvt_pk_bf16_f32 v29, v35, v37
	v_cvt_pk_bf16_f32 v30, v39, v41
	v_cvt_pk_bf16_f32 v31, v43, v47
	v_lshl_add_u64 v[14:15], v[44:45], 0, v[14:15]
	global_store_dwordx4 v[14:15], v[28:31], off
	s_waitcnt lgkmcnt(0)
	s_branch .LBB0_18

.LBB0_59:
	s_mul_hi_i32 s22, s3, 0x2aaaaaab
	s_lshr_b32 s23, s22, 31
	s_ashr_i32 s21, s22, 4
	s_add_i32 s21, s21, s23
	s_lshl_b32 s29, s21, 6
	v_or_b32_e32 v2, s29, v26
	v_ashrrev_i32_e32 v3, 31, v2
	v_lshl_add_u64 v[2:3], v[2:3], 2, s[26:27]
	s_ashr_i32 s28, s29, 31
	global_load_dword v21, v[2:3], off nt
	v_mov_b32_e32 v3, s28
	v_or_b32_e32 v2, s29, v26
	v_lshl_add_u64 v[2:3], v[2:3], 2, s[24:25]
	v_add_co_u32_e32 v4, vcc, s12, v2
	global_load_dword v24, v[2:3], off nt
	s_nop 0
	v_addc_co_u32_e32 v5, vcc, 0, v3, vcc
	v_add_co_u32_e32 v2, vcc, s13, v2
	s_ashr_i32 s22, s22, 2
	s_nop 0
	v_addc_co_u32_e32 v3, vcc, 0, v3, vcc
	global_load_dword v25, v[4:5], off offset:-4096 nt
	global_load_dword v30, v[4:5], off nt
	global_load_dword v31, v[2:3], off nt
	s_add_i32 s23, s22, s23
	s_and_b32 s22, s23, 3
	s_mul_i32 s30, s21, 0x180000
	s_mul_i32 s34, s22, 0x1800000
	s_mul_hi_i32 s29, s29, 0x6000
	s_add_u32 s30, s34, s30
	v_lshl_or_b32 v22, s3, 8, v1
	s_mul_i32 s31, s23, 0x1800
	s_addc_u32 s29, 0, s29
	v_subrev_u32_e32 v22, s31, v22
	s_add_u32 s30, s10, s30
	v_ashrrev_i32_e32 v23, 31, v22
	s_addc_u32 s31, s11, s29
	v_lshl_add_u64 v[28:29], v[22:23], 2, s[30:31]
	s_mov_b32 s28, 0
	v_mov_b32_e32 v2, 0
	v_mov_b32_e32 v3, v32
	v_mov_b32_e32 v4, 0
	v_mov_b32_e32 v5, v32
	v_mov_b32_e32 v6, 0
	v_mov_b32_e32 v7, v32
	v_mov_b32_e32 v8, 0
	v_mov_b32_e32 v9, v32
	v_mov_b32_e32 v10, 0
	v_mov_b32_e32 v11, v32
	v_mov_b32_e32 v12, 0
	v_mov_b32_e32 v13, v32
	v_mov_b32_e32 v14, 0
	v_mov_b32_e32 v15, v32
	v_mov_b32_e32 v16, 0
	v_mov_b32_e32 v17, v32
	v_mov_b32_e32 v18, 0
	v_mov_b32_e32 v19, v32
	v_mov_b32_e32 v20, 0
	s_waitcnt vmcnt(4)
	v_mul_f32_e32 v22, 0xbfb8aa3b, v21
	v_exp_f32_e32 v22, v22
	s_waitcnt vmcnt(3)
	v_mul_f32_e32 v23, 0xbfb8aa3b, v24
	v_exp_f32_e32 v23, v23
	v_add_f32_e32 v22, 1.0, v22
	v_rcp_f32_e32 v22, v22
	v_add_f32_e32 v23, 1.0, v23
	s_waitcnt vmcnt(2)
	v_mul_f32_e32 v35, 0xbfb8aa3b, v25
	s_waitcnt vmcnt(1)
	v_mul_f32_e32 v36, 0xbfb8aa3b, v30
	s_waitcnt vmcnt(0)
	v_mul_f32_e32 v37, 0xbfb8aa3b, v31
	v_exp_f32_e32 v35, v35
	v_exp_f32_e32 v36, v36
	v_exp_f32_e32 v37, v37
	v_rcp_f32_e32 v23, v23
	v_add_f32_e32 v35, 1.0, v35
	v_add_f32_e32 v36, 1.0, v36
	v_add_f32_e32 v37, 1.0, v37
	v_rcp_f32_e32 v38, v35
	v_rcp_f32_e32 v39, v36
	v_rcp_f32_e32 v40, v37
	v_mul_f32_e32 v35, v21, v22
	v_mul_f32_e32 v36, v24, v23
	v_mul_f32_e32 v37, v25, v38
	v_mul_f32_e32 v38, v30, v39
	v_mul_f32_e32 v39, v31, v40
	v_mov_b32_e32 v21, v32
.LBB0_60:
	v_add_co_u32_e32 v30, vcc, s15, v28
	global_load_dwordx4 v[22:25], v[28:29], off nt
	s_nop 0
	v_addc_co_u32_e32 v31, vcc, -1, v29, vcc
	v_add_co_u32_e32 v56, vcc, s16, v28
	v_add_u32_e32 v71, s28, v33
	s_nop 0
	v_addc_co_u32_e32 v57, vcc, -1, v29, vcc
	v_add_co_u32_e32 v58, vcc, s17, v28
	ds_bpermute_b32 v70, v71, v36
	s_nop 0
	v_addc_co_u32_e32 v59, vcc, -1, v29, vcc
	v_add_co_u32_e32 v60, vcc, s18, v28
	ds_bpermute_b32 v72, v71, v37
	s_nop 0
	v_addc_co_u32_e32 v61, vcc, -1, v29, vcc
	v_add_co_u32_e32 v64, vcc, s14, v28
	global_load_dwordx4 v[40:43], v[30:31], off nt
	global_load_dwordx4 v[44:47], v[56:57], off nt
	global_load_dwordx4 v[48:51], v[58:59], off nt
	global_load_dwordx4 v[52:55], v[60:61], off nt
	v_addc_co_u32_e32 v65, vcc, 0, v29, vcc
	v_add_co_u32_e32 v66, vcc, s19, v28
	ds_bpermute_b32 v30, v71, v35
	s_nop 0
	v_addc_co_u32_e32 v67, vcc, 0, v29, vcc
	v_add_co_u32_e32 v68, vcc, s20, v28
	global_load_dwordx4 v[56:59], v[64:65], off nt
	global_load_dwordx4 v[60:63], v[66:67], off nt
	v_addc_co_u32_e32 v69, vcc, 0, v29, vcc
	global_load_dwordx4 v[64:67], v[68:69], off nt
	ds_bpermute_b32 v74, v71, v38
	ds_bpermute_b32 v76, v71, v39
	ds_bpermute_b32 v78, v71, v35 offset:4
	ds_bpermute_b32 v80, v71, v36 offset:4
	ds_bpermute_b32 v82, v71, v37 offset:4
	ds_bpermute_b32 v84, v71, v38 offset:4
	ds_bpermute_b32 v86, v71, v39 offset:4
	ds_bpermute_b32 v88, v71, v35 offset:8
	ds_bpermute_b32 v90, v71, v36 offset:8
	ds_bpermute_b32 v92, v71, v37 offset:8
	ds_bpermute_b32 v94, v71, v38 offset:8
	ds_bpermute_b32 v68, v71, v39 offset:8
	ds_bpermute_b32 v96, v71, v35 offset:12
	ds_bpermute_b32 v98, v71, v36 offset:12
	ds_bpermute_b32 v100, v71, v37 offset:12
	ds_bpermute_b32 v102, v71, v38 offset:12
	ds_bpermute_b32 v104, v71, v39 offset:12
	ds_bpermute_b32 v106, v71, v35 offset:16
	ds_bpermute_b32 v108, v71, v36 offset:16
	ds_bpermute_b32 v110, v71, v37 offset:16
	ds_bpermute_b32 v112, v71, v38 offset:16
	ds_bpermute_b32 v114, v71, v39 offset:16
	ds_bpermute_b32 v116, v71, v35 offset:20
	ds_bpermute_b32 v118, v71, v36 offset:20
	ds_bpermute_b32 v120, v71, v37 offset:20
	ds_bpermute_b32 v122, v71, v38 offset:20
	ds_bpermute_b32 v124, v71, v39 offset:20
	ds_bpermute_b32 v126, v71, v35 offset:24
	ds_bpermute_b32 v128, v71, v36 offset:24
	ds_bpermute_b32 v130, v71, v37 offset:24
	ds_bpermute_b32 v132, v71, v38 offset:24
	ds_bpermute_b32 v134, v71, v39 offset:24
	ds_bpermute_b32 v136, v71, v35 offset:28
	ds_bpermute_b32 v138, v71, v36 offset:28
	ds_bpermute_b32 v140, v71, v37 offset:28
	ds_bpermute_b32 v142, v71, v38 offset:28
	ds_bpermute_b32 v144, v71, v39 offset:28
	s_add_i32 s28, s28, 32
	v_lshl_add_u64 v[28:29], v[28:29], 0, s[8:9]
	s_cmpk_eq_i32 s28, 0x100
	s_waitcnt vmcnt(6) lgkmcnt(14)
	v_pk_fma_f32 v[8:9], v[42:43], v[30:31], v[8:9] op_sel_hi:[1,0,1]
	v_pk_fma_f32 v[6:7], v[40:41], v[30:31], v[6:7] op_sel_hi:[1,0,1]
	v_pk_fma_f32 v[12:13], v[42:43], v[70:71], v[12:13] op_sel_hi:[1,0,1]
	v_pk_fma_f32 v[10:11], v[40:41], v[70:71], v[10:11] op_sel_hi:[1,0,1]
	v_pk_fma_f32 v[16:17], v[42:43], v[72:73], v[16:17] op_sel_hi:[1,0,1]
	v_pk_fma_f32 v[14:15], v[40:41], v[72:73], v[14:15] op_sel_hi:[1,0,1]
	v_pk_fma_f32 v[20:21], v[42:43], v[74:75], v[20:21] op_sel_hi:[1,0,1]
	v_pk_fma_f32 v[18:19], v[40:41], v[74:75], v[18:19] op_sel_hi:[1,0,1]
	v_pk_fma_f32 v[4:5], v[42:43], v[76:77], v[4:5] op_sel_hi:[1,0,1]
	v_pk_fma_f32 v[2:3], v[40:41], v[76:77], v[2:3] op_sel_hi:[1,0,1]
	s_waitcnt vmcnt(5)
	v_pk_fma_f32 v[8:9], v[46:47], v[78:79], v[8:9] op_sel_hi:[1,0,1]
	v_pk_fma_f32 v[6:7], v[44:45], v[78:79], v[6:7] op_sel_hi:[1,0,1]
	v_pk_fma_f32 v[12:13], v[46:47], v[80:81], v[12:13] op_sel_hi:[1,0,1]
	v_pk_fma_f32 v[10:11], v[44:45], v[80:81], v[10:11] op_sel_hi:[1,0,1]
	v_pk_fma_f32 v[16:17], v[46:47], v[82:83], v[16:17] op_sel_hi:[1,0,1]
	v_pk_fma_f32 v[14:15], v[44:45], v[82:83], v[14:15] op_sel_hi:[1,0,1]
	v_pk_fma_f32 v[20:21], v[46:47], v[84:85], v[20:21] op_sel_hi:[1,0,1]
	v_pk_fma_f32 v[18:19], v[44:45], v[84:85], v[18:19] op_sel_hi:[1,0,1]
	v_pk_fma_f32 v[4:5], v[46:47], v[86:87], v[4:5] op_sel_hi:[1,0,1]
	v_pk_fma_f32 v[2:3], v[44:45], v[86:87], v[2:3] op_sel_hi:[1,0,1]
	s_waitcnt vmcnt(4)
	v_pk_fma_f32 v[8:9], v[50:51], v[88:89], v[8:9] op_sel_hi:[1,0,1]
	v_pk_fma_f32 v[6:7], v[48:49], v[88:89], v[6:7] op_sel_hi:[1,0,1]
	v_pk_fma_f32 v[12:13], v[50:51], v[90:91], v[12:13] op_sel_hi:[1,0,1]
	v_pk_fma_f32 v[10:11], v[48:49], v[90:91], v[10:11] op_sel_hi:[1,0,1]
	v_pk_fma_f32 v[16:17], v[50:51], v[92:93], v[16:17] op_sel_hi:[1,0,1]
	v_pk_fma_f32 v[14:15], v[48:49], v[92:93], v[14:15] op_sel_hi:[1,0,1]
	v_pk_fma_f32 v[20:21], v[50:51], v[94:95], v[20:21] op_sel_hi:[1,0,1]
	v_pk_fma_f32 v[18:19], v[48:49], v[94:95], v[18:19] op_sel_hi:[1,0,1]
	v_pk_fma_f32 v[4:5], v[50:51], v[68:69], v[4:5] op_sel_hi:[1,0,1]
	v_pk_fma_f32 v[2:3], v[48:49], v[68:69], v[2:3] op_sel_hi:[1,0,1]
	s_waitcnt vmcnt(3)
	v_pk_fma_f32 v[8:9], v[54:55], v[96:97], v[8:9] op_sel_hi:[1,0,1]
	v_pk_fma_f32 v[6:7], v[52:53], v[96:97], v[6:7] op_sel_hi:[1,0,1]
	v_pk_fma_f32 v[12:13], v[54:55], v[98:99], v[12:13] op_sel_hi:[1,0,1]
	v_pk_fma_f32 v[10:11], v[52:53], v[98:99], v[10:11] op_sel_hi:[1,0,1]
	v_pk_fma_f32 v[16:17], v[54:55], v[100:101], v[16:17] op_sel_hi:[1,0,1]
	v_pk_fma_f32 v[14:15], v[52:53], v[100:101], v[14:15] op_sel_hi:[1,0,1]
	v_pk_fma_f32 v[20:21], v[54:55], v[102:103], v[20:21] op_sel_hi:[1,0,1]
	v_pk_fma_f32 v[18:19], v[52:53], v[102:103], v[18:19] op_sel_hi:[1,0,1]
	v_pk_fma_f32 v[4:5], v[54:55], v[104:105], v[4:5] op_sel_hi:[1,0,1]
	v_pk_fma_f32 v[2:3], v[52:53], v[104:105], v[2:3] op_sel_hi:[1,0,1]
	v_pk_fma_f32 v[8:9], v[24:25], v[106:107], v[8:9] op_sel_hi:[1,0,1]
	v_pk_fma_f32 v[6:7], v[22:23], v[106:107], v[6:7] op_sel_hi:[1,0,1]
	v_pk_fma_f32 v[12:13], v[24:25], v[108:109], v[12:13] op_sel_hi:[1,0,1]
	v_pk_fma_f32 v[10:11], v[22:23], v[108:109], v[10:11] op_sel_hi:[1,0,1]
	v_pk_fma_f32 v[16:17], v[24:25], v[110:111], v[16:17] op_sel_hi:[1,0,1]
	v_pk_fma_f32 v[14:15], v[22:23], v[110:111], v[14:15] op_sel_hi:[1,0,1]
	v_pk_fma_f32 v[20:21], v[24:25], v[112:113], v[20:21] op_sel_hi:[1,0,1]
	v_pk_fma_f32 v[18:19], v[22:23], v[112:113], v[18:19] op_sel_hi:[1,0,1]
	v_pk_fma_f32 v[4:5], v[24:25], v[114:115], v[4:5] op_sel_hi:[1,0,1]
	v_pk_fma_f32 v[2:3], v[22:23], v[114:115], v[2:3] op_sel_hi:[1,0,1]
	s_waitcnt vmcnt(2)
	v_pk_fma_f32 v[8:9], v[58:59], v[116:117], v[8:9] op_sel_hi:[1,0,1]
	v_pk_fma_f32 v[6:7], v[56:57], v[116:117], v[6:7] op_sel_hi:[1,0,1]
	s_waitcnt lgkmcnt(13)
	v_pk_fma_f32 v[12:13], v[58:59], v[118:119], v[12:13] op_sel_hi:[1,0,1]
	v_pk_fma_f32 v[10:11], v[56:57], v[118:119], v[10:11] op_sel_hi:[1,0,1]
	s_waitcnt lgkmcnt(12)
	v_pk_fma_f32 v[16:17], v[58:59], v[120:121], v[16:17] op_sel_hi:[1,0,1]
	v_pk_fma_f32 v[14:15], v[56:57], v[120:121], v[14:15] op_sel_hi:[1,0,1]
	s_waitcnt lgkmcnt(11)
	v_pk_fma_f32 v[20:21], v[58:59], v[122:123], v[20:21] op_sel_hi:[1,0,1]
	v_pk_fma_f32 v[18:19], v[56:57], v[122:123], v[18:19] op_sel_hi:[1,0,1]
	s_waitcnt lgkmcnt(10)
	v_pk_fma_f32 v[4:5], v[58:59], v[124:125], v[4:5] op_sel_hi:[1,0,1]
	v_pk_fma_f32 v[2:3], v[56:57], v[124:125], v[2:3] op_sel_hi:[1,0,1]
	s_waitcnt vmcnt(1) lgkmcnt(9)
	v_pk_fma_f32 v[8:9], v[62:63], v[126:127], v[8:9] op_sel_hi:[1,0,1]
	v_pk_fma_f32 v[6:7], v[60:61], v[126:127], v[6:7] op_sel_hi:[1,0,1]
	s_waitcnt lgkmcnt(8)
	v_pk_fma_f32 v[12:13], v[62:63], v[128:129], v[12:13] op_sel_hi:[1,0,1]
	v_pk_fma_f32 v[10:11], v[60:61], v[128:129], v[10:11] op_sel_hi:[1,0,1]
	s_waitcnt lgkmcnt(7)
	v_pk_fma_f32 v[16:17], v[62:63], v[130:131], v[16:17] op_sel_hi:[1,0,1]
	v_pk_fma_f32 v[14:15], v[60:61], v[130:131], v[14:15] op_sel_hi:[1,0,1]
	s_waitcnt lgkmcnt(6)
	v_pk_fma_f32 v[20:21], v[62:63], v[132:133], v[20:21] op_sel_hi:[1,0,1]
	v_pk_fma_f32 v[18:19], v[60:61], v[132:133], v[18:19] op_sel_hi:[1,0,1]
	s_waitcnt lgkmcnt(5)
	v_pk_fma_f32 v[4:5], v[62:63], v[134:135], v[4:5] op_sel_hi:[1,0,1]
	v_pk_fma_f32 v[2:3], v[60:61], v[134:135], v[2:3] op_sel_hi:[1,0,1]
	s_waitcnt vmcnt(0) lgkmcnt(4)
	v_pk_fma_f32 v[8:9], v[66:67], v[136:137], v[8:9] op_sel_hi:[1,0,1]
	v_pk_fma_f32 v[6:7], v[64:65], v[136:137], v[6:7] op_sel_hi:[1,0,1]
	s_waitcnt lgkmcnt(3)
	v_pk_fma_f32 v[12:13], v[66:67], v[138:139], v[12:13] op_sel_hi:[1,0,1]
	v_pk_fma_f32 v[10:11], v[64:65], v[138:139], v[10:11] op_sel_hi:[1,0,1]
	s_waitcnt lgkmcnt(2)
	v_pk_fma_f32 v[16:17], v[66:67], v[140:141], v[16:17] op_sel_hi:[1,0,1]
	v_pk_fma_f32 v[14:15], v[64:65], v[140:141], v[14:15] op_sel_hi:[1,0,1]
	s_waitcnt lgkmcnt(1)
	v_pk_fma_f32 v[20:21], v[66:67], v[142:143], v[20:21] op_sel_hi:[1,0,1]
	v_pk_fma_f32 v[18:19], v[64:65], v[142:143], v[18:19] op_sel_hi:[1,0,1]
	s_waitcnt lgkmcnt(0)
	v_pk_fma_f32 v[4:5], v[66:67], v[144:145], v[4:5] op_sel_hi:[1,0,1]
	v_pk_fma_f32 v[2:3], v[64:65], v[144:145], v[2:3] op_sel_hi:[1,0,1]
	s_cbranch_scc0 .LBB0_60
	s_mul_i32 s23, s23, 24
	s_sub_i32 s23, s3, s23
	v_lshl_or_b32 v22, s23, 8, v1
	s_lshl_b32 s21, s21, 2
	v_ashrrev_i32_e32 v23, 31, v22
	s_or_b32 s21, s21, s22
	s_mul_i32 s21, s21, 5
	v_lshl_add_u64 v[22:23], v[22:23], 2, s[6:7]
	v_mad_i64_i32 v[24:25], s[22:23], s21, v34, v[22:23]
	s_add_i32 s22, s21, 1
	global_store_dwordx4 v[24:25], v[6:9], off
	s_add_i32 s3, s3, s76
	s_nop 0
	v_mad_i64_i32 v[6:7], s[22:23], s22, v34, v[22:23]
	s_add_i32 s22, s21, 2
	global_store_dwordx4 v[6:7], v[10:13], off
	v_mad_i64_i32 v[6:7], s[22:23], s22, v34, v[22:23]
	s_add_i32 s22, s21, 3
	global_store_dwordx4 v[6:7], v[14:17], off
	v_mad_i64_i32 v[6:7], s[22:23], s22, v34, v[22:23]
	s_add_i32 s21, s21, 4
	global_store_dwordx4 v[6:7], v[18:21], off
	v_mad_i64_i32 v[6:7], s[22:23], s21, v34, v[22:23]
	s_cmpk_gt_i32 s3, 0x5ff
	global_store_dwordx4 v[6:7], v[2:5], off
	s_cbranch_scc0 .LBB0_59
